# RWKV scan: removed 154 broadcast v_mov copies (use op_sel hi-broadcast on packed ops)
# speedup vs baseline: 1.0071x; 1.0071x over previous
.LBB0_595:
	s_andn2_saveexec_b64 s[0:1], s[20:21]
	s_cbranch_execz .LBB0_609
	s_bitcmp1_b32 s25, 0
	s_cselect_b32 s20, 0x6000, 0
	v_add_u32_e32 v1, s20, v143
	ds_read_b128 v[32:35], v1
	ds_read_b128 v[40:43], v1 offset:16
	s_and_b32 s20, s25, 1
	s_mul_i32 s21, s20, 0x6000
	s_add_i32 s21, s21, 0
	s_waitcnt lgkmcnt(1)
	v_pk_mul_f32 v[2:3], v[66:67], v[34:35] op_sel_hi:[1,0]
	v_pk_mul_f32 v[34:35], v[64:65], v[34:35] op_sel:[0,1]
	v_pk_fma_f32 v[2:3], v[70:71], v[32:33], v[2:3] op_sel_hi:[1,0,1]
	v_pk_fma_f32 v[32:33], v[68:69], v[32:33], v[34:35] op_sel:[0,1,0]
	s_waitcnt lgkmcnt(0)
	v_pk_fma_f32 v[2:3], v[62:63], v[40:41], v[2:3] op_sel_hi:[1,0,1]
	v_pk_fma_f32 v[32:33], v[60:61], v[40:41], v[32:33] op_sel:[0,1,0]
	v_pk_fma_f32 v[2:3], v[46:47], v[42:43], v[2:3] op_sel_hi:[1,0,1]
	v_pk_fma_f32 v[32:33], v[44:45], v[42:43], v[32:33] op_sel:[0,1,0]
	v_lshl_add_u32 v152, v97, 2, s21
	v_pk_add_f32 v[2:3], v[2:3], v[32:33]
	v_lshl_add_u32 v151, v98, 2, s21
	ds_read_b128 v[72:75], v152 offset:4096
	ds_read_b128 v[154:157], v152 offset:4112
	ds_read_b128 v[158:161], v152 offset:8192
	ds_read_b128 v[166:169], v152 offset:8208
	ds_read_b128 v[170:173], v152 offset:12288
	ds_read_b128 v[174:177], v152 offset:12304
	ds_read_b128 v[178:181], v152 offset:16384
	ds_read_b128 v[198:201], v152 offset:16400
	ds_read_b64 v[202:203], v151 offset:20480
	ds_read_b128 v[36:39], v1 offset:256
	ds_read_b128 v[28:31], v1 offset:272
	v_mov_b32_dpp v32, v2 quad_perm:[1,0,3,2] row_mask:0xf bank_mask:0xf bound_ctrl:1
	v_mov_b32_dpp v33, v3 quad_perm:[1,0,3,2] row_mask:0xf bank_mask:0xf bound_ctrl:1
	v_pk_add_f32 v[2:3], v[2:3], v[32:33]
	s_lshl_b32 s20, s20, 12
	v_add_u32_e32 v153, s20, v99
	v_mov_b32_dpp v32, v2 quad_perm:[2,3,0,1] row_mask:0xf bank_mask:0xf bound_ctrl:1
	v_mov_b32_dpp v33, v3 quad_perm:[2,3,0,1] row_mask:0xf bank_mask:0xf bound_ctrl:1
	v_pk_add_f32 v[2:3], v[2:3], v[32:33]
	s_nop 1
	v_mov_b32_dpp v32, v2 row_half_mirror row_mask:0xf bank_mask:0xf bound_ctrl:1
	v_mov_b32_dpp v33, v3 row_half_mirror row_mask:0xf bank_mask:0xf bound_ctrl:1
	v_pk_add_f32 v[32:33], v[2:3], v[32:33]
	s_waitcnt lgkmcnt(8)
	v_pk_mul_f32 v[2:3], v[158:159], v[32:33] op_sel_hi:[0,1]
	s_waitcnt lgkmcnt(2)
	v_pk_fma_f32 v[2:3], v[170:171], v[202:203], v[2:3] op_sel_hi:[0,1,1] neg_lo:[0,0,1] neg_hi:[0,0,1]
	v_pk_mul_f32 v[34:35], v[158:159], v[32:33] op_sel:[1,0]
	v_pk_fma_f32 v[2:3], v[70:71], v[72:73], v[2:3] op_sel_hi:[1,0,1]
	v_pk_fma_f32 v[34:35], v[170:171], v[202:203], v[34:35] op_sel:[1,0,0] neg_lo:[0,0,1] neg_hi:[0,0,1]
	v_pk_mul_f32 v[42:43], v[160:161], v[32:33] op_sel_hi:[0,1]
	v_pk_fma_f32 v[68:69], v[68:69], v[72:73], v[34:35] op_sel:[0,1,0]
	v_pk_fma_f32 v[42:43], v[172:173], v[202:203], v[42:43] op_sel_hi:[0,1,1] neg_lo:[0,0,1] neg_hi:[0,0,1]
	v_pk_mul_f32 v[70:71], v[160:161], v[32:33] op_sel:[1,0]
	v_pk_fma_f32 v[66:67], v[66:67], v[74:75], v[42:43] op_sel_hi:[1,0,1]
	v_pk_fma_f32 v[70:71], v[172:173], v[202:203], v[70:71] op_sel:[1,0,0] neg_lo:[0,0,1] neg_hi:[0,0,1]
	v_pk_fma_f32 v[40:41], v[178:179], v[68:69], 0 op_sel:[1,0,0] op_sel_hi:[1,1,0]
	v_pk_fma_f32 v[64:65], v[64:65], v[74:75], v[70:71] op_sel:[0,1,0]
	v_pk_fma_f32 v[40:41], v[180:181], v[64:65], v[40:41] op_sel:[1,0,0]
	v_pk_mul_f32 v[42:43], v[166:167], v[32:33] op_sel_hi:[0,1]
	v_pk_fma_f32 v[42:43], v[174:175], v[202:203], v[42:43] op_sel_hi:[0,1,1] neg_lo:[0,0,1] neg_hi:[0,0,1]
	v_pk_fma_f32 v[62:63], v[62:63], v[154:155], v[42:43] op_sel_hi:[1,0,1]
	v_pk_mul_f32 v[42:43], v[166:167], v[32:33] op_sel:[1,0]
	v_pk_fma_f32 v[34:35], v[178:179], v[2:3], 0 op_sel_hi:[0,1,0]
	v_pk_fma_f32 v[42:43], v[174:175], v[202:203], v[42:43] op_sel:[1,0,0] neg_lo:[0,0,1] neg_hi:[0,0,1]
	v_pk_fma_f32 v[60:61], v[60:61], v[154:155], v[42:43] op_sel:[0,1,0]
	v_pk_mul_f32 v[42:43], v[168:169], v[32:33] op_sel_hi:[0,1]
	v_pk_fma_f32 v[34:35], v[180:181], v[66:67], v[34:35] op_sel_hi:[0,1,1]
	v_pk_fma_f32 v[42:43], v[176:177], v[202:203], v[42:43] op_sel_hi:[0,1,1] neg_lo:[0,0,1] neg_hi:[0,0,1]
	v_pk_mul_f32 v[32:33], v[168:169], v[32:33] op_sel:[1,0]
	v_pk_fma_f32 v[34:35], v[198:199], v[62:63], v[34:35] op_sel_hi:[0,1,1]
	v_pk_fma_f32 v[46:47], v[46:47], v[156:157], v[42:43] op_sel_hi:[1,0,1]
	v_pk_fma_f32 v[32:33], v[176:177], v[202:203], v[32:33] op_sel:[1,0,0] neg_lo:[0,0,1] neg_hi:[0,0,1]
	v_pk_fma_f32 v[40:41], v[198:199], v[60:61], v[40:41] op_sel:[1,0,0]
	v_pk_fma_f32 v[44:45], v[44:45], v[156:157], v[32:33] op_sel:[0,1,0]
	v_pk_fma_f32 v[32:33], v[200:201], v[46:47], v[34:35] op_sel_hi:[0,1,1]
	v_pk_fma_f32 v[34:35], v[200:201], v[44:45], v[40:41] op_sel:[1,0,0]
	v_pk_add_f32 v[32:33], v[32:33], v[34:35]
	s_nop 1
	v_mov_b32_dpp v34, v32 quad_perm:[1,0,3,2] row_mask:0xf bank_mask:0xf bound_ctrl:1
	v_mov_b32_dpp v35, v33 quad_perm:[1,0,3,2] row_mask:0xf bank_mask:0xf bound_ctrl:1
	v_pk_add_f32 v[32:33], v[32:33], v[34:35]
	s_nop 1
	v_mov_b32_dpp v34, v32 quad_perm:[2,3,0,1] row_mask:0xf bank_mask:0xf bound_ctrl:1
	v_mov_b32_dpp v35, v33 quad_perm:[2,3,0,1] row_mask:0xf bank_mask:0xf bound_ctrl:1
	v_pk_add_f32 v[32:33], v[32:33], v[34:35]
	s_nop 1
	v_mov_b32_dpp v34, v32 row_half_mirror row_mask:0xf bank_mask:0xf bound_ctrl:1
	v_mov_b32_dpp v35, v33 row_half_mirror row_mask:0xf bank_mask:0xf bound_ctrl:1
	s_and_saveexec_b64 s[20:21], s[14:15]
	v_pk_add_f32 v[32:33], v[32:33], v[34:35]
	ds_write_b64 v153, v[32:33] offset:49152
	s_or_b64 exec, exec, s[20:21]
	s_waitcnt lgkmcnt(1)
	v_pk_mul_f32 v[202:203], v[38:39], v[66:67] op_sel_hi:[0,1]
	v_pk_fma_f32 v[202:203], v[36:37], v[2:3], v[202:203] op_sel_hi:[0,1,1]
	v_pk_mul_f32 v[38:39], v[38:39], v[64:65] op_sel:[1,0]
	v_pk_fma_f32 v[36:37], v[36:37], v[68:69], v[38:39] op_sel:[1,0,0]
	s_waitcnt lgkmcnt(0)
	v_pk_fma_f32 v[38:39], v[28:29], v[62:63], v[202:203] op_sel_hi:[0,1,1]
	v_pk_fma_f32 v[28:29], v[28:29], v[60:61], v[36:37] op_sel:[1,0,0]
	v_pk_fma_f32 v[36:37], v[30:31], v[46:47], v[38:39] op_sel_hi:[0,1,1]
	v_pk_fma_f32 v[28:29], v[30:31], v[44:45], v[28:29] op_sel:[1,0,0]
	v_pk_add_f32 v[28:29], v[36:37], v[28:29]
	ds_read_b128 v[70:73], v152 offset:4352
	ds_read_b128 v[154:157], v152 offset:4368
	ds_read_b128 v[158:161], v152 offset:8448
	ds_read_b128 v[166:169], v152 offset:8464
	ds_read_b128 v[170:173], v152 offset:12544
	ds_read_b128 v[174:177], v152 offset:12560
	ds_read_b128 v[178:181], v152 offset:16640
	ds_read_b128 v[198:201], v152 offset:16656
	ds_read_b64 v[74:75], v151 offset:20736
	ds_read_b128 v[40:43], v1 offset:512
	ds_read_b128 v[32:35], v1 offset:528
	v_mov_b32_dpp v30, v28 quad_perm:[1,0,3,2] row_mask:0xf bank_mask:0xf bound_ctrl:1
	v_mov_b32_dpp v31, v29 quad_perm:[1,0,3,2] row_mask:0xf bank_mask:0xf bound_ctrl:1
	v_pk_add_f32 v[28:29], v[28:29], v[30:31]
	s_nop 1
	v_mov_b32_dpp v30, v28 quad_perm:[2,3,0,1] row_mask:0xf bank_mask:0xf bound_ctrl:1
	v_mov_b32_dpp v31, v29 quad_perm:[2,3,0,1] row_mask:0xf bank_mask:0xf bound_ctrl:1
	v_pk_add_f32 v[28:29], v[28:29], v[30:31]
	s_nop 1
	v_mov_b32_dpp v30, v28 row_half_mirror row_mask:0xf bank_mask:0xf bound_ctrl:1
	v_mov_b32_dpp v31, v29 row_half_mirror row_mask:0xf bank_mask:0xf bound_ctrl:1
	v_pk_add_f32 v[28:29], v[28:29], v[30:31]
	s_waitcnt lgkmcnt(8)
	v_pk_mul_f32 v[30:31], v[158:159], v[28:29] op_sel_hi:[0,1]
	s_waitcnt lgkmcnt(2)
	v_pk_fma_f32 v[30:31], v[170:171], v[74:75], v[30:31] op_sel_hi:[0,1,1] neg_lo:[0,0,1] neg_hi:[0,0,1]
	v_pk_fma_f32 v[2:3], v[2:3], v[70:71], v[30:31] op_sel_hi:[1,0,1]
	v_pk_mul_f32 v[30:31], v[158:159], v[28:29] op_sel:[1,0]
	v_pk_mul_f32 v[38:39], v[160:161], v[28:29] op_sel_hi:[0,1]
	v_pk_fma_f32 v[30:31], v[170:171], v[74:75], v[30:31] op_sel:[1,0,0] neg_lo:[0,0,1] neg_hi:[0,0,1]
	v_pk_fma_f32 v[38:39], v[172:173], v[74:75], v[38:39] op_sel_hi:[0,1,1] neg_lo:[0,0,1] neg_hi:[0,0,1]
	v_pk_fma_f32 v[68:69], v[68:69], v[70:71], v[30:31] op_sel:[0,1,0]
	v_pk_fma_f32 v[66:67], v[66:67], v[72:73], v[38:39] op_sel_hi:[1,0,1]
	v_pk_mul_f32 v[70:71], v[160:161], v[28:29] op_sel:[1,0]
	v_pk_fma_f32 v[70:71], v[172:173], v[74:75], v[70:71] op_sel:[1,0,0] neg_lo:[0,0,1] neg_hi:[0,0,1]
	v_pk_fma_f32 v[36:37], v[178:179], v[68:69], 0 op_sel:[1,0,0] op_sel_hi:[1,1,0]
	v_pk_fma_f32 v[64:65], v[64:65], v[72:73], v[70:71] op_sel:[0,1,0]
	v_pk_fma_f32 v[36:37], v[180:181], v[64:65], v[36:37] op_sel:[1,0,0]
	v_pk_mul_f32 v[38:39], v[166:167], v[28:29] op_sel_hi:[0,1]
	v_pk_fma_f32 v[38:39], v[174:175], v[74:75], v[38:39] op_sel_hi:[0,1,1] neg_lo:[0,0,1] neg_hi:[0,0,1]
	v_pk_fma_f32 v[62:63], v[62:63], v[154:155], v[38:39] op_sel_hi:[1,0,1]
	v_pk_mul_f32 v[38:39], v[166:167], v[28:29] op_sel:[1,0]
	v_pk_fma_f32 v[30:31], v[178:179], v[2:3], 0 op_sel_hi:[0,1,0]
	v_pk_fma_f32 v[38:39], v[174:175], v[74:75], v[38:39] op_sel:[1,0,0] neg_lo:[0,0,1] neg_hi:[0,0,1]
	v_pk_fma_f32 v[60:61], v[60:61], v[154:155], v[38:39] op_sel:[0,1,0]
	v_pk_mul_f32 v[38:39], v[168:169], v[28:29] op_sel_hi:[0,1]
	v_pk_fma_f32 v[30:31], v[180:181], v[66:67], v[30:31] op_sel_hi:[0,1,1]
	v_pk_fma_f32 v[38:39], v[176:177], v[74:75], v[38:39] op_sel_hi:[0,1,1] neg_lo:[0,0,1] neg_hi:[0,0,1]
	v_pk_mul_f32 v[28:29], v[168:169], v[28:29] op_sel:[1,0]
	v_pk_fma_f32 v[30:31], v[198:199], v[62:63], v[30:31] op_sel_hi:[0,1,1]
	v_pk_fma_f32 v[46:47], v[46:47], v[156:157], v[38:39] op_sel_hi:[1,0,1]
	v_pk_fma_f32 v[28:29], v[176:177], v[74:75], v[28:29] op_sel:[1,0,0] neg_lo:[0,0,1] neg_hi:[0,0,1]
	v_pk_fma_f32 v[36:37], v[198:199], v[60:61], v[36:37] op_sel:[1,0,0]
	v_pk_fma_f32 v[44:45], v[44:45], v[156:157], v[28:29] op_sel:[0,1,0]
	v_pk_fma_f32 v[28:29], v[200:201], v[46:47], v[30:31] op_sel_hi:[0,1,1]
	v_pk_fma_f32 v[30:31], v[200:201], v[44:45], v[36:37] op_sel:[1,0,0]
	v_pk_add_f32 v[28:29], v[28:29], v[30:31]
	s_nop 1
	v_mov_b32_dpp v30, v28 quad_perm:[1,0,3,2] row_mask:0xf bank_mask:0xf bound_ctrl:1
	v_mov_b32_dpp v31, v29 quad_perm:[1,0,3,2] row_mask:0xf bank_mask:0xf bound_ctrl:1
	v_pk_add_f32 v[28:29], v[28:29], v[30:31]
	s_nop 1
	v_mov_b32_dpp v30, v28 quad_perm:[2,3,0,1] row_mask:0xf bank_mask:0xf bound_ctrl:1
	v_mov_b32_dpp v31, v29 quad_perm:[2,3,0,1] row_mask:0xf bank_mask:0xf bound_ctrl:1
	v_pk_add_f32 v[28:29], v[28:29], v[30:31]
	s_nop 1
	v_mov_b32_dpp v30, v28 row_half_mirror row_mask:0xf bank_mask:0xf bound_ctrl:1
	v_mov_b32_dpp v31, v29 row_half_mirror row_mask:0xf bank_mask:0xf bound_ctrl:1
	s_and_saveexec_b64 s[20:21], s[14:15]
	v_pk_add_f32 v[28:29], v[28:29], v[30:31]
	ds_write_b64 v153, v[28:29] offset:49408
	s_or_b64 exec, exec, s[20:21]
	s_waitcnt lgkmcnt(1)
	v_pk_mul_f32 v[202:203], v[42:43], v[66:67] op_sel_hi:[0,1]
	v_pk_fma_f32 v[202:203], v[40:41], v[2:3], v[202:203] op_sel_hi:[0,1,1]
	v_pk_mul_f32 v[42:43], v[42:43], v[64:65] op_sel:[1,0]
	v_pk_fma_f32 v[40:41], v[40:41], v[68:69], v[42:43] op_sel:[1,0,0]
	s_waitcnt lgkmcnt(0)
	v_pk_fma_f32 v[42:43], v[32:33], v[62:63], v[202:203] op_sel_hi:[0,1,1]
	v_pk_fma_f32 v[32:33], v[32:33], v[60:61], v[40:41] op_sel:[1,0,0]
	v_pk_fma_f32 v[40:41], v[34:35], v[46:47], v[42:43] op_sel_hi:[0,1,1]
	v_pk_fma_f32 v[32:33], v[34:35], v[44:45], v[32:33] op_sel:[1,0,0]
	v_pk_add_f32 v[32:33], v[40:41], v[32:33]
	ds_read_b128 v[70:73], v152 offset:4608
	ds_read_b128 v[154:157], v152 offset:4624
	ds_read_b128 v[158:161], v152 offset:8704
	ds_read_b128 v[166:169], v152 offset:8720
	ds_read_b128 v[170:173], v152 offset:12800
	ds_read_b128 v[174:177], v152 offset:12816
	ds_read_b128 v[178:181], v152 offset:16896
	ds_read_b128 v[198:201], v152 offset:16912
	ds_read_b64 v[74:75], v151 offset:20992
	ds_read_b128 v[36:39], v1 offset:768
	ds_read_b128 v[28:31], v1 offset:784
	v_mov_b32_dpp v34, v32 quad_perm:[1,0,3,2] row_mask:0xf bank_mask:0xf bound_ctrl:1
	v_mov_b32_dpp v35, v33 quad_perm:[1,0,3,2] row_mask:0xf bank_mask:0xf bound_ctrl:1
	v_pk_add_f32 v[32:33], v[32:33], v[34:35]
	s_nop 1
	v_mov_b32_dpp v34, v32 quad_perm:[2,3,0,1] row_mask:0xf bank_mask:0xf bound_ctrl:1
	v_mov_b32_dpp v35, v33 quad_perm:[2,3,0,1] row_mask:0xf bank_mask:0xf bound_ctrl:1
	v_pk_add_f32 v[32:33], v[32:33], v[34:35]
	s_nop 1
	v_mov_b32_dpp v34, v32 row_half_mirror row_mask:0xf bank_mask:0xf bound_ctrl:1
	v_mov_b32_dpp v35, v33 row_half_mirror row_mask:0xf bank_mask:0xf bound_ctrl:1
	v_pk_add_f32 v[32:33], v[32:33], v[34:35]
	s_waitcnt lgkmcnt(8)
	v_pk_mul_f32 v[34:35], v[158:159], v[32:33] op_sel_hi:[0,1]
	s_waitcnt lgkmcnt(2)
	v_pk_fma_f32 v[34:35], v[170:171], v[74:75], v[34:35] op_sel_hi:[0,1,1] neg_lo:[0,0,1] neg_hi:[0,0,1]
	v_pk_fma_f32 v[2:3], v[2:3], v[70:71], v[34:35] op_sel_hi:[1,0,1]
	v_pk_mul_f32 v[34:35], v[158:159], v[32:33] op_sel:[1,0]
	v_pk_mul_f32 v[42:43], v[160:161], v[32:33] op_sel_hi:[0,1]
	v_pk_fma_f32 v[34:35], v[170:171], v[74:75], v[34:35] op_sel:[1,0,0] neg_lo:[0,0,1] neg_hi:[0,0,1]
	v_pk_fma_f32 v[42:43], v[172:173], v[74:75], v[42:43] op_sel_hi:[0,1,1] neg_lo:[0,0,1] neg_hi:[0,0,1]
	v_pk_fma_f32 v[68:69], v[68:69], v[70:71], v[34:35] op_sel:[0,1,0]
	v_pk_fma_f32 v[66:67], v[66:67], v[72:73], v[42:43] op_sel_hi:[1,0,1]
	v_pk_mul_f32 v[70:71], v[160:161], v[32:33] op_sel:[1,0]
	v_pk_fma_f32 v[70:71], v[172:173], v[74:75], v[70:71] op_sel:[1,0,0] neg_lo:[0,0,1] neg_hi:[0,0,1]
	v_pk_fma_f32 v[40:41], v[178:179], v[68:69], 0 op_sel:[1,0,0] op_sel_hi:[1,1,0]
	v_pk_fma_f32 v[64:65], v[64:65], v[72:73], v[70:71] op_sel:[0,1,0]
	v_pk_fma_f32 v[40:41], v[180:181], v[64:65], v[40:41] op_sel:[1,0,0]
	v_pk_mul_f32 v[42:43], v[166:167], v[32:33] op_sel_hi:[0,1]
	v_pk_fma_f32 v[42:43], v[174:175], v[74:75], v[42:43] op_sel_hi:[0,1,1] neg_lo:[0,0,1] neg_hi:[0,0,1]
	v_pk_fma_f32 v[62:63], v[62:63], v[154:155], v[42:43] op_sel_hi:[1,0,1]
	v_pk_mul_f32 v[42:43], v[166:167], v[32:33] op_sel:[1,0]
	v_pk_fma_f32 v[34:35], v[178:179], v[2:3], 0 op_sel_hi:[0,1,0]
	v_pk_fma_f32 v[42:43], v[174:175], v[74:75], v[42:43] op_sel:[1,0,0] neg_lo:[0,0,1] neg_hi:[0,0,1]
	v_pk_fma_f32 v[60:61], v[60:61], v[154:155], v[42:43] op_sel:[0,1,0]
	v_pk_mul_f32 v[42:43], v[168:169], v[32:33] op_sel_hi:[0,1]
	v_pk_fma_f32 v[34:35], v[180:181], v[66:67], v[34:35] op_sel_hi:[0,1,1]
	v_pk_fma_f32 v[42:43], v[176:177], v[74:75], v[42:43] op_sel_hi:[0,1,1] neg_lo:[0,0,1] neg_hi:[0,0,1]
	v_pk_mul_f32 v[32:33], v[168:169], v[32:33] op_sel:[1,0]
	v_pk_fma_f32 v[34:35], v[198:199], v[62:63], v[34:35] op_sel_hi:[0,1,1]
	v_pk_fma_f32 v[46:47], v[46:47], v[156:157], v[42:43] op_sel_hi:[1,0,1]
	v_pk_fma_f32 v[32:33], v[176:177], v[74:75], v[32:33] op_sel:[1,0,0] neg_lo:[0,0,1] neg_hi:[0,0,1]
	v_pk_fma_f32 v[40:41], v[198:199], v[60:61], v[40:41] op_sel:[1,0,0]
	v_pk_fma_f32 v[44:45], v[44:45], v[156:157], v[32:33] op_sel:[0,1,0]
	v_pk_fma_f32 v[32:33], v[200:201], v[46:47], v[34:35] op_sel_hi:[0,1,1]
	v_pk_fma_f32 v[34:35], v[200:201], v[44:45], v[40:41] op_sel:[1,0,0]
	v_pk_add_f32 v[32:33], v[32:33], v[34:35]
	s_nop 1
	v_mov_b32_dpp v34, v32 quad_perm:[1,0,3,2] row_mask:0xf bank_mask:0xf bound_ctrl:1
	v_mov_b32_dpp v35, v33 quad_perm:[1,0,3,2] row_mask:0xf bank_mask:0xf bound_ctrl:1
	v_pk_add_f32 v[32:33], v[32:33], v[34:35]
	s_nop 1
	v_mov_b32_dpp v34, v32 quad_perm:[2,3,0,1] row_mask:0xf bank_mask:0xf bound_ctrl:1
	v_mov_b32_dpp v35, v33 quad_perm:[2,3,0,1] row_mask:0xf bank_mask:0xf bound_ctrl:1
	v_pk_add_f32 v[32:33], v[32:33], v[34:35]
	s_nop 1
	v_mov_b32_dpp v34, v32 row_half_mirror row_mask:0xf bank_mask:0xf bound_ctrl:1
	v_mov_b32_dpp v35, v33 row_half_mirror row_mask:0xf bank_mask:0xf bound_ctrl:1
	s_and_saveexec_b64 s[20:21], s[14:15]
	v_pk_add_f32 v[32:33], v[32:33], v[34:35]
	ds_write_b64 v153, v[32:33] offset:49664
	s_or_b64 exec, exec, s[20:21]
	s_waitcnt lgkmcnt(1)
	v_pk_mul_f32 v[202:203], v[38:39], v[66:67] op_sel_hi:[0,1]
	v_pk_fma_f32 v[202:203], v[36:37], v[2:3], v[202:203] op_sel_hi:[0,1,1]
	v_pk_mul_f32 v[38:39], v[38:39], v[64:65] op_sel:[1,0]
	v_pk_fma_f32 v[36:37], v[36:37], v[68:69], v[38:39] op_sel:[1,0,0]
	s_waitcnt lgkmcnt(0)
	v_pk_fma_f32 v[38:39], v[28:29], v[62:63], v[202:203] op_sel_hi:[0,1,1]
	v_pk_fma_f32 v[28:29], v[28:29], v[60:61], v[36:37] op_sel:[1,0,0]
	v_pk_fma_f32 v[36:37], v[30:31], v[46:47], v[38:39] op_sel_hi:[0,1,1]
	v_pk_fma_f32 v[28:29], v[30:31], v[44:45], v[28:29] op_sel:[1,0,0]
	v_pk_add_f32 v[28:29], v[36:37], v[28:29]
	ds_read_b128 v[70:73], v152 offset:4864
	ds_read_b128 v[154:157], v152 offset:4880
	ds_read_b128 v[158:161], v152 offset:8960
	ds_read_b128 v[166:169], v152 offset:8976
	ds_read_b128 v[170:173], v152 offset:13056
	ds_read_b128 v[174:177], v152 offset:13072
	ds_read_b128 v[178:181], v152 offset:17152
	ds_read_b128 v[198:201], v152 offset:17168
	ds_read_b64 v[74:75], v151 offset:21248
	ds_read_b128 v[40:43], v1 offset:1024
	ds_read_b128 v[32:35], v1 offset:1040
	v_mov_b32_dpp v30, v28 quad_perm:[1,0,3,2] row_mask:0xf bank_mask:0xf bound_ctrl:1
	v_mov_b32_dpp v31, v29 quad_perm:[1,0,3,2] row_mask:0xf bank_mask:0xf bound_ctrl:1
	v_pk_add_f32 v[28:29], v[28:29], v[30:31]
	s_nop 1
	v_mov_b32_dpp v30, v28 quad_perm:[2,3,0,1] row_mask:0xf bank_mask:0xf bound_ctrl:1
	v_mov_b32_dpp v31, v29 quad_perm:[2,3,0,1] row_mask:0xf bank_mask:0xf bound_ctrl:1
	v_pk_add_f32 v[28:29], v[28:29], v[30:31]
	s_nop 1
	v_mov_b32_dpp v30, v28 row_half_mirror row_mask:0xf bank_mask:0xf bound_ctrl:1
	v_mov_b32_dpp v31, v29 row_half_mirror row_mask:0xf bank_mask:0xf bound_ctrl:1
	v_pk_add_f32 v[36:37], v[28:29], v[30:31]
	s_waitcnt lgkmcnt(8)
	v_pk_mul_f32 v[28:29], v[158:159], v[36:37] op_sel_hi:[0,1]
	s_waitcnt lgkmcnt(2)
	v_pk_fma_f32 v[28:29], v[170:171], v[74:75], v[28:29] op_sel_hi:[0,1,1] neg_lo:[0,0,1] neg_hi:[0,0,1]
	v_pk_fma_f32 v[2:3], v[2:3], v[70:71], v[28:29] op_sel_hi:[1,0,1]
	v_pk_mul_f32 v[28:29], v[158:159], v[36:37] op_sel:[1,0]
	v_pk_mul_f32 v[30:31], v[160:161], v[36:37] op_sel_hi:[0,1]
	v_pk_fma_f32 v[28:29], v[170:171], v[74:75], v[28:29] op_sel:[1,0,0] neg_lo:[0,0,1] neg_hi:[0,0,1]
	v_pk_fma_f32 v[30:31], v[172:173], v[74:75], v[30:31] op_sel_hi:[0,1,1] neg_lo:[0,0,1] neg_hi:[0,0,1]
	v_pk_fma_f32 v[28:29], v[68:69], v[70:71], v[28:29] op_sel:[0,1,0]
	v_pk_fma_f32 v[30:31], v[66:67], v[72:73], v[30:31] op_sel_hi:[1,0,1]
	v_pk_mul_f32 v[70:71], v[160:161], v[36:37] op_sel:[1,0]
	v_pk_fma_f32 v[70:71], v[172:173], v[74:75], v[70:71] op_sel:[1,0,0] neg_lo:[0,0,1] neg_hi:[0,0,1]
	v_pk_fma_f32 v[68:69], v[178:179], v[28:29], 0 op_sel:[1,0,0] op_sel_hi:[1,1,0]
	v_pk_fma_f32 v[64:65], v[64:65], v[72:73], v[70:71] op_sel:[0,1,0]
	v_pk_fma_f32 v[66:67], v[180:181], v[64:65], v[68:69] op_sel:[1,0,0]
	v_pk_mul_f32 v[68:69], v[166:167], v[36:37] op_sel_hi:[0,1]
	v_pk_fma_f32 v[68:69], v[174:175], v[74:75], v[68:69] op_sel_hi:[0,1,1] neg_lo:[0,0,1] neg_hi:[0,0,1]
	v_pk_fma_f32 v[62:63], v[62:63], v[154:155], v[68:69] op_sel_hi:[1,0,1]
	v_pk_mul_f32 v[68:69], v[166:167], v[36:37] op_sel:[1,0]
	v_pk_fma_f32 v[38:39], v[178:179], v[2:3], 0 op_sel_hi:[0,1,0]
	v_pk_fma_f32 v[68:69], v[174:175], v[74:75], v[68:69] op_sel:[1,0,0] neg_lo:[0,0,1] neg_hi:[0,0,1]
	v_pk_fma_f32 v[38:39], v[180:181], v[30:31], v[38:39] op_sel_hi:[0,1,1]
	v_pk_fma_f32 v[60:61], v[60:61], v[154:155], v[68:69] op_sel:[0,1,0]
	v_pk_fma_f32 v[70:71], v[198:199], v[60:61], v[66:67] op_sel:[1,0,0]
	v_pk_mul_f32 v[66:67], v[168:169], v[36:37] op_sel_hi:[0,1]
	v_pk_fma_f32 v[66:67], v[176:177], v[74:75], v[66:67] op_sel_hi:[0,1,1] neg_lo:[0,0,1] neg_hi:[0,0,1]
	v_pk_mul_f32 v[36:37], v[168:169], v[36:37] op_sel:[1,0]
	v_pk_fma_f32 v[38:39], v[198:199], v[62:63], v[38:39] op_sel_hi:[0,1,1]
	v_pk_fma_f32 v[66:67], v[46:47], v[156:157], v[66:67] op_sel_hi:[1,0,1]
	v_pk_fma_f32 v[36:37], v[176:177], v[74:75], v[36:37] op_sel:[1,0,0] neg_lo:[0,0,1] neg_hi:[0,0,1]
	v_pk_fma_f32 v[68:69], v[44:45], v[156:157], v[36:37] op_sel:[0,1,0]
	v_pk_fma_f32 v[36:37], v[200:201], v[66:67], v[38:39] op_sel_hi:[0,1,1]
	v_pk_fma_f32 v[38:39], v[200:201], v[68:69], v[70:71] op_sel:[1,0,0]
	v_pk_add_f32 v[36:37], v[36:37], v[38:39]
	s_nop 1
	v_mov_b32_dpp v38, v36 quad_perm:[1,0,3,2] row_mask:0xf bank_mask:0xf bound_ctrl:1
	v_mov_b32_dpp v39, v37 quad_perm:[1,0,3,2] row_mask:0xf bank_mask:0xf bound_ctrl:1
	v_pk_add_f32 v[36:37], v[36:37], v[38:39]
	s_nop 1
	v_mov_b32_dpp v38, v36 quad_perm:[2,3,0,1] row_mask:0xf bank_mask:0xf bound_ctrl:1
	v_mov_b32_dpp v39, v37 quad_perm:[2,3,0,1] row_mask:0xf bank_mask:0xf bound_ctrl:1
	v_pk_add_f32 v[36:37], v[36:37], v[38:39]
	s_nop 1
	v_mov_b32_dpp v38, v36 row_half_mirror row_mask:0xf bank_mask:0xf bound_ctrl:1
	v_mov_b32_dpp v39, v37 row_half_mirror row_mask:0xf bank_mask:0xf bound_ctrl:1
	s_and_saveexec_b64 s[20:21], s[14:15]
	v_pk_add_f32 v[36:37], v[36:37], v[38:39]
	ds_write_b64 v153, v[36:37] offset:49920
	s_or_b64 exec, exec, s[20:21]
	s_waitcnt lgkmcnt(1)
	v_pk_mul_f32 v[202:203], v[42:43], v[30:31] op_sel_hi:[0,1]
	v_pk_fma_f32 v[202:203], v[40:41], v[2:3], v[202:203] op_sel_hi:[0,1,1]
	v_pk_mul_f32 v[42:43], v[42:43], v[64:65] op_sel:[1,0]
	v_pk_fma_f32 v[40:41], v[40:41], v[28:29], v[42:43] op_sel:[1,0,0]
	s_waitcnt lgkmcnt(0)
	v_pk_fma_f32 v[42:43], v[32:33], v[62:63], v[202:203] op_sel_hi:[0,1,1]
	v_pk_fma_f32 v[32:33], v[32:33], v[60:61], v[40:41] op_sel:[1,0,0]
	v_pk_fma_f32 v[40:41], v[34:35], v[66:67], v[42:43] op_sel_hi:[0,1,1]
	v_pk_fma_f32 v[32:33], v[34:35], v[68:69], v[32:33] op_sel:[1,0,0]
	v_pk_add_f32 v[32:33], v[40:41], v[32:33]
	ds_read_b128 v[70:73], v152 offset:5120
	ds_read_b128 v[154:157], v152 offset:5136
	ds_read_b128 v[158:161], v152 offset:9216
	ds_read_b128 v[166:169], v152 offset:9232
	ds_read_b128 v[170:173], v152 offset:13312
	ds_read_b128 v[174:177], v152 offset:13328
	ds_read_b128 v[178:181], v152 offset:17408
	ds_read_b128 v[198:201], v152 offset:17424
	ds_read_b64 v[74:75], v151 offset:21504
	ds_read_b128 v[44:47], v1 offset:1280
	ds_read_b128 v[36:39], v1 offset:1296
	v_mov_b32_dpp v34, v32 quad_perm:[1,0,3,2] row_mask:0xf bank_mask:0xf bound_ctrl:1
	v_mov_b32_dpp v35, v33 quad_perm:[1,0,3,2] row_mask:0xf bank_mask:0xf bound_ctrl:1
	v_pk_add_f32 v[32:33], v[32:33], v[34:35]
	s_nop 1
	v_mov_b32_dpp v34, v32 quad_perm:[2,3,0,1] row_mask:0xf bank_mask:0xf bound_ctrl:1
	v_mov_b32_dpp v35, v33 quad_perm:[2,3,0,1] row_mask:0xf bank_mask:0xf bound_ctrl:1
	v_pk_add_f32 v[32:33], v[32:33], v[34:35]
	s_nop 1
	v_mov_b32_dpp v34, v32 row_half_mirror row_mask:0xf bank_mask:0xf bound_ctrl:1
	v_mov_b32_dpp v35, v33 row_half_mirror row_mask:0xf bank_mask:0xf bound_ctrl:1
	v_pk_add_f32 v[32:33], v[32:33], v[34:35]
	s_waitcnt lgkmcnt(8)
	v_pk_mul_f32 v[34:35], v[158:159], v[32:33] op_sel_hi:[0,1]
	s_waitcnt lgkmcnt(2)
	v_pk_fma_f32 v[34:35], v[170:171], v[74:75], v[34:35] op_sel_hi:[0,1,1] neg_lo:[0,0,1] neg_hi:[0,0,1]
	v_pk_fma_f32 v[2:3], v[2:3], v[70:71], v[34:35] op_sel_hi:[1,0,1]
	v_pk_mul_f32 v[34:35], v[158:159], v[32:33] op_sel:[1,0]
	v_pk_mul_f32 v[42:43], v[160:161], v[32:33] op_sel_hi:[0,1]
	v_pk_fma_f32 v[34:35], v[170:171], v[74:75], v[34:35] op_sel:[1,0,0] neg_lo:[0,0,1] neg_hi:[0,0,1]
	v_pk_fma_f32 v[42:43], v[172:173], v[74:75], v[42:43] op_sel_hi:[0,1,1] neg_lo:[0,0,1] neg_hi:[0,0,1]
	v_pk_fma_f32 v[40:41], v[28:29], v[70:71], v[34:35] op_sel:[0,1,0]
	v_pk_fma_f32 v[42:43], v[30:31], v[72:73], v[42:43] op_sel_hi:[1,0,1]
	v_pk_mul_f32 v[70:71], v[160:161], v[32:33] op_sel:[1,0]
	v_pk_fma_f32 v[70:71], v[172:173], v[74:75], v[70:71] op_sel:[1,0,0] neg_lo:[0,0,1] neg_hi:[0,0,1]
	v_pk_fma_f32 v[34:35], v[178:179], v[40:41], 0 op_sel:[1,0,0] op_sel_hi:[1,1,0]
	v_pk_fma_f32 v[64:65], v[64:65], v[72:73], v[70:71] op_sel:[0,1,0]
	v_pk_fma_f32 v[30:31], v[180:181], v[64:65], v[34:35] op_sel:[1,0,0]
	v_pk_mul_f32 v[34:35], v[166:167], v[32:33] op_sel_hi:[0,1]
	v_pk_fma_f32 v[34:35], v[174:175], v[74:75], v[34:35] op_sel_hi:[0,1,1] neg_lo:[0,0,1] neg_hi:[0,0,1]
	v_pk_fma_f32 v[62:63], v[62:63], v[154:155], v[34:35] op_sel_hi:[1,0,1]
	v_pk_mul_f32 v[34:35], v[166:167], v[32:33] op_sel:[1,0]
	v_pk_fma_f32 v[28:29], v[178:179], v[2:3], 0 op_sel_hi:[0,1,0]
	v_pk_fma_f32 v[34:35], v[174:175], v[74:75], v[34:35] op_sel:[1,0,0] neg_lo:[0,0,1] neg_hi:[0,0,1]
	v_pk_fma_f32 v[60:61], v[60:61], v[154:155], v[34:35] op_sel:[0,1,0]
	v_pk_mul_f32 v[34:35], v[168:169], v[32:33] op_sel_hi:[0,1]
	v_pk_fma_f32 v[34:35], v[176:177], v[74:75], v[34:35] op_sel_hi:[0,1,1] neg_lo:[0,0,1] neg_hi:[0,0,1]
	v_pk_fma_f32 v[72:73], v[66:67], v[156:157], v[34:35] op_sel_hi:[1,0,1]
	v_pk_mul_f32 v[32:33], v[168:169], v[32:33] op_sel:[1,0]
	v_pk_fma_f32 v[28:29], v[180:181], v[42:43], v[28:29] op_sel_hi:[0,1,1]
	v_pk_fma_f32 v[32:33], v[176:177], v[74:75], v[32:33] op_sel:[1,0,0] neg_lo:[0,0,1] neg_hi:[0,0,1]
	v_pk_fma_f32 v[28:29], v[198:199], v[62:63], v[28:29] op_sel_hi:[0,1,1]
	v_pk_fma_f32 v[30:31], v[198:199], v[60:61], v[30:31] op_sel:[1,0,0]
	v_pk_fma_f32 v[74:75], v[68:69], v[156:157], v[32:33] op_sel:[0,1,0]
	v_pk_fma_f32 v[28:29], v[200:201], v[72:73], v[28:29] op_sel_hi:[0,1,1]
	v_pk_fma_f32 v[30:31], v[200:201], v[74:75], v[30:31] op_sel:[1,0,0]
	v_pk_add_f32 v[28:29], v[28:29], v[30:31]
	s_nop 1
	v_mov_b32_dpp v30, v28 quad_perm:[1,0,3,2] row_mask:0xf bank_mask:0xf bound_ctrl:1
	v_mov_b32_dpp v31, v29 quad_perm:[1,0,3,2] row_mask:0xf bank_mask:0xf bound_ctrl:1
	v_pk_add_f32 v[28:29], v[28:29], v[30:31]
	s_nop 1
	v_mov_b32_dpp v30, v28 quad_perm:[2,3,0,1] row_mask:0xf bank_mask:0xf bound_ctrl:1
	v_mov_b32_dpp v31, v29 quad_perm:[2,3,0,1] row_mask:0xf bank_mask:0xf bound_ctrl:1
	v_pk_add_f32 v[28:29], v[28:29], v[30:31]
	s_nop 1
	v_mov_b32_dpp v30, v28 row_half_mirror row_mask:0xf bank_mask:0xf bound_ctrl:1
	v_mov_b32_dpp v31, v29 row_half_mirror row_mask:0xf bank_mask:0xf bound_ctrl:1
	s_and_saveexec_b64 s[20:21], s[14:15]
	v_pk_add_f32 v[28:29], v[28:29], v[30:31]
	ds_write_b64 v153, v[28:29] offset:50176
	s_or_b64 exec, exec, s[20:21]
	s_waitcnt lgkmcnt(1)
	v_pk_mul_f32 v[66:67], v[46:47], v[42:43] op_sel_hi:[0,1]
	v_pk_fma_f32 v[66:67], v[44:45], v[2:3], v[66:67] op_sel_hi:[0,1,1]
	v_pk_mul_f32 v[46:47], v[46:47], v[64:65] op_sel:[1,0]
	v_pk_fma_f32 v[44:45], v[44:45], v[40:41], v[46:47] op_sel:[1,0,0]
	s_waitcnt lgkmcnt(0)
	v_pk_fma_f32 v[46:47], v[36:37], v[62:63], v[66:67] op_sel_hi:[0,1,1]
	v_pk_fma_f32 v[36:37], v[36:37], v[60:61], v[44:45] op_sel:[1,0,0]
	v_pk_fma_f32 v[44:45], v[38:39], v[72:73], v[46:47] op_sel_hi:[0,1,1]
	v_pk_fma_f32 v[36:37], v[38:39], v[74:75], v[36:37] op_sel:[1,0,0]
	v_pk_add_f32 v[36:37], v[44:45], v[36:37]
	ds_read_b128 v[154:157], v152 offset:5376
	ds_read_b128 v[158:161], v152 offset:5392
	ds_read_b128 v[166:169], v152 offset:9472
	ds_read_b128 v[170:173], v152 offset:9488
	ds_read_b128 v[174:177], v152 offset:13568
	ds_read_b128 v[178:181], v152 offset:13584
	ds_read_b128 v[198:201], v152 offset:17664
	ds_read_b128 v[202:205], v152 offset:17680
	ds_read_b64 v[206:207], v151 offset:21760
	ds_read_b128 v[32:35], v1 offset:1536
	ds_read_b128 v[28:31], v1 offset:1552
	v_mov_b32_dpp v38, v36 quad_perm:[1,0,3,2] row_mask:0xf bank_mask:0xf bound_ctrl:1
	v_mov_b32_dpp v39, v37 quad_perm:[1,0,3,2] row_mask:0xf bank_mask:0xf bound_ctrl:1
	v_pk_add_f32 v[36:37], v[36:37], v[38:39]
	s_waitcnt lgkmcnt(6)
	v_mov_b32_dpp v38, v36 quad_perm:[2,3,0,1] row_mask:0xf bank_mask:0xf bound_ctrl:1
	v_mov_b32_dpp v39, v37 quad_perm:[2,3,0,1] row_mask:0xf bank_mask:0xf bound_ctrl:1
	v_pk_add_f32 v[36:37], v[36:37], v[38:39]
	s_nop 1
	v_mov_b32_dpp v38, v36 row_half_mirror row_mask:0xf bank_mask:0xf bound_ctrl:1
	v_mov_b32_dpp v39, v37 row_half_mirror row_mask:0xf bank_mask:0xf bound_ctrl:1
	v_pk_add_f32 v[36:37], v[36:37], v[38:39]
	s_nop 0
	v_pk_mul_f32 v[38:39], v[166:167], v[36:37] op_sel_hi:[0,1]
	s_waitcnt lgkmcnt(2)
	v_pk_fma_f32 v[38:39], v[174:175], v[206:207], v[38:39] op_sel_hi:[0,1,1] neg_lo:[0,0,1] neg_hi:[0,0,1]
	v_pk_fma_f32 v[70:71], v[2:3], v[154:155], v[38:39] op_sel_hi:[1,0,1]
	v_pk_mul_f32 v[2:3], v[166:167], v[36:37] op_sel:[1,0]
	s_nop 0
	v_pk_fma_f32 v[2:3], v[174:175], v[206:207], v[2:3] op_sel:[1,0,0] neg_lo:[0,0,1] neg_hi:[0,0,1]
	s_nop 0
	v_pk_fma_f32 v[68:69], v[40:41], v[154:155], v[2:3] op_sel:[0,1,0]
	v_pk_mul_f32 v[40:41], v[168:169], v[36:37] op_sel_hi:[0,1]
	v_pk_fma_f32 v[40:41], v[176:177], v[206:207], v[40:41] op_sel_hi:[0,1,1] neg_lo:[0,0,1] neg_hi:[0,0,1]
	v_pk_fma_f32 v[66:67], v[42:43], v[156:157], v[40:41] op_sel_hi:[1,0,1]
	v_pk_mul_f32 v[42:43], v[168:169], v[36:37] op_sel:[1,0]
	v_pk_fma_f32 v[42:43], v[176:177], v[206:207], v[42:43] op_sel:[1,0,0] neg_lo:[0,0,1] neg_hi:[0,0,1]
	v_pk_fma_f32 v[38:39], v[198:199], v[68:69], 0 op_sel:[1,0,0] op_sel_hi:[1,1,0]
	v_pk_fma_f32 v[64:65], v[64:65], v[156:157], v[42:43] op_sel:[0,1,0]
	v_pk_fma_f32 v[38:39], v[200:201], v[64:65], v[38:39] op_sel:[1,0,0]
	v_pk_mul_f32 v[40:41], v[170:171], v[36:37] op_sel_hi:[0,1]
	v_pk_fma_f32 v[40:41], v[178:179], v[206:207], v[40:41] op_sel_hi:[0,1,1] neg_lo:[0,0,1] neg_hi:[0,0,1]
	v_pk_fma_f32 v[62:63], v[62:63], v[158:159], v[40:41] op_sel_hi:[1,0,1]
	v_pk_mul_f32 v[40:41], v[170:171], v[36:37] op_sel:[1,0]
	v_mov_b32_e32 v42, v173
	v_pk_fma_f32 v[40:41], v[178:179], v[206:207], v[40:41] op_sel:[1,0,0] neg_lo:[0,0,1] neg_hi:[0,0,1]
	v_pk_fma_f32 v[2:3], v[198:199], v[70:71], 0 op_sel_hi:[0,1,0]
	v_pk_fma_f32 v[60:61], v[60:61], v[158:159], v[40:41] op_sel:[0,1,0]
	v_pk_mul_f32 v[40:41], v[172:173], v[36:37] op_sel_hi:[0,1]
	v_pk_fma_f32 v[40:41], v[180:181], v[206:207], v[40:41] op_sel_hi:[0,1,1] neg_lo:[0,0,1] neg_hi:[0,0,1]
	v_pk_mul_f32 v[36:37], v[42:43], v[36:37] op_sel_hi:[0,1]
	v_pk_fma_f32 v[2:3], v[200:201], v[66:67], v[2:3] op_sel_hi:[0,1,1]
	v_pk_fma_f32 v[46:47], v[72:73], v[160:161], v[40:41] op_sel_hi:[1,0,1]
	v_mov_b32_e32 v40, v161
	v_pk_fma_f32 v[36:37], v[180:181], v[206:207], v[36:37] op_sel:[1,0,0] neg_lo:[0,0,1] neg_hi:[0,0,1]
	v_pk_fma_f32 v[2:3], v[202:203], v[62:63], v[2:3] op_sel_hi:[0,1,1]
	v_pk_fma_f32 v[38:39], v[202:203], v[60:61], v[38:39] op_sel:[1,0,0]
	v_pk_fma_f32 v[44:45], v[74:75], v[40:41], v[36:37] op_sel_hi:[1,0,1]
	v_pk_fma_f32 v[2:3], v[204:205], v[46:47], v[2:3] op_sel_hi:[0,1,1]
	v_pk_fma_f32 v[36:37], v[204:205], v[44:45], v[38:39] op_sel:[1,0,0]
	v_pk_add_f32 v[2:3], v[2:3], v[36:37]
	s_nop 1
	v_mov_b32_dpp v36, v2 quad_perm:[1,0,3,2] row_mask:0xf bank_mask:0xf bound_ctrl:1
	v_mov_b32_dpp v37, v3 quad_perm:[1,0,3,2] row_mask:0xf bank_mask:0xf bound_ctrl:1
	v_pk_add_f32 v[2:3], v[2:3], v[36:37]
	s_nop 1
	v_mov_b32_dpp v36, v2 quad_perm:[2,3,0,1] row_mask:0xf bank_mask:0xf bound_ctrl:1
	v_mov_b32_dpp v37, v3 quad_perm:[2,3,0,1] row_mask:0xf bank_mask:0xf bound_ctrl:1
	v_pk_add_f32 v[2:3], v[2:3], v[36:37]
	s_nop 1
	v_mov_b32_dpp v36, v2 row_half_mirror row_mask:0xf bank_mask:0xf bound_ctrl:1
	v_mov_b32_dpp v37, v3 row_half_mirror row_mask:0xf bank_mask:0xf bound_ctrl:1
	s_and_saveexec_b64 s[20:21], s[14:15]
	v_pk_add_f32 v[2:3], v[2:3], v[36:37]
	ds_write_b64 v153, v[2:3] offset:50432
	s_or_b64 exec, exec, s[20:21]

.LBB0_612:
	s_andn2_saveexec_b64 s[0:1], s[0:1]
	s_cbranch_execz .LBB0_624
	v_pk_mul_f32 v[2:3], v[66:67], v[34:35] op_sel_hi:[1,0]
	v_pk_fma_f32 v[2:3], v[70:71], v[32:33], v[2:3] op_sel_hi:[1,0,1]
	v_pk_mul_f32 v[34:35], v[64:65], v[34:35] op_sel:[0,1]
	v_pk_fma_f32 v[2:3], v[62:63], v[28:29], v[2:3] op_sel_hi:[1,0,1]
	v_pk_fma_f32 v[32:33], v[68:69], v[32:33], v[34:35] op_sel:[0,1,0]
	v_pk_fma_f32 v[2:3], v[46:47], v[30:31], v[2:3] op_sel_hi:[1,0,1]
	v_pk_fma_f32 v[28:29], v[60:61], v[28:29], v[32:33] op_sel:[0,1,0]
	v_pk_fma_f32 v[28:29], v[44:45], v[30:31], v[28:29] op_sel:[0,1,0]
	s_and_b32 s20, s25, 1
	v_pk_add_f32 v[2:3], v[2:3], v[28:29]
	s_mul_i32 s21, s20, 0x6000
	s_add_i32 s21, s21, 0
	v_mov_b32_dpp v28, v2 quad_perm:[1,0,3,2] row_mask:0xf bank_mask:0xf bound_ctrl:1
	v_mov_b32_dpp v29, v3 quad_perm:[1,0,3,2] row_mask:0xf bank_mask:0xf bound_ctrl:1
	v_pk_add_f32 v[2:3], v[2:3], v[28:29]
	s_bitcmp1_b32 s25, 0
	v_lshl_add_u32 v152, v97, 2, s21
	v_mov_b32_dpp v28, v2 quad_perm:[2,3,0,1] row_mask:0xf bank_mask:0xf bound_ctrl:1
	v_mov_b32_dpp v29, v3 quad_perm:[2,3,0,1] row_mask:0xf bank_mask:0xf bound_ctrl:1
	v_lshl_add_u32 v1, v98, 2, s21
	s_cselect_b32 s21, 0x6000, 0
	v_pk_add_f32 v[2:3], v[2:3], v[28:29]
	v_add_u32_e32 v151, s21, v143
	ds_read_b128 v[72:75], v152 offset:5632
	ds_read_b128 v[154:157], v152 offset:5648
	ds_read_b128 v[158:161], v152 offset:9728
	ds_read_b128 v[166:169], v152 offset:9744
	ds_read_b128 v[170:173], v152 offset:13824
	ds_read_b128 v[174:177], v152 offset:13840
	ds_read_b128 v[178:181], v152 offset:17920
	ds_read_b128 v[198:201], v152 offset:17936
	ds_read_b64 v[202:203], v1 offset:22016
	ds_read_b128 v[40:43], v151 offset:1792
	ds_read_b128 v[36:39], v151 offset:1808
	v_mov_b32_dpp v28, v2 row_half_mirror row_mask:0xf bank_mask:0xf bound_ctrl:1
	v_mov_b32_dpp v29, v3 row_half_mirror row_mask:0xf bank_mask:0xf bound_ctrl:1
	v_pk_add_f32 v[28:29], v[2:3], v[28:29]
	s_lshl_b32 s20, s20, 12
	s_waitcnt lgkmcnt(8)
	v_pk_mul_f32 v[2:3], v[158:159], v[28:29] op_sel_hi:[0,1]
	s_waitcnt lgkmcnt(2)
	v_pk_fma_f32 v[2:3], v[170:171], v[202:203], v[2:3] op_sel_hi:[0,1,1] neg_lo:[0,0,1] neg_hi:[0,0,1]
	v_pk_mul_f32 v[30:31], v[158:159], v[28:29] op_sel:[1,0]
	v_pk_fma_f32 v[2:3], v[70:71], v[72:73], v[2:3] op_sel_hi:[1,0,1]
	v_pk_fma_f32 v[30:31], v[170:171], v[202:203], v[30:31] op_sel:[1,0,0] neg_lo:[0,0,1] neg_hi:[0,0,1]
	v_pk_mul_f32 v[34:35], v[160:161], v[28:29] op_sel_hi:[0,1]
	v_pk_fma_f32 v[32:33], v[68:69], v[72:73], v[30:31] op_sel:[0,1,0]
	v_pk_fma_f32 v[34:35], v[172:173], v[202:203], v[34:35] op_sel_hi:[0,1,1] neg_lo:[0,0,1] neg_hi:[0,0,1]
	v_pk_mul_f32 v[70:71], v[160:161], v[28:29] op_sel:[1,0]
	v_pk_fma_f32 v[34:35], v[66:67], v[74:75], v[34:35] op_sel_hi:[1,0,1]
	v_pk_fma_f32 v[70:71], v[172:173], v[202:203], v[70:71] op_sel:[1,0,0] neg_lo:[0,0,1] neg_hi:[0,0,1]
	v_pk_fma_f32 v[68:69], v[178:179], v[32:33], 0 op_sel:[1,0,0] op_sel_hi:[1,1,0]
	v_pk_fma_f32 v[64:65], v[64:65], v[74:75], v[70:71] op_sel:[0,1,0]
	v_pk_fma_f32 v[66:67], v[180:181], v[64:65], v[68:69] op_sel:[1,0,0]
	v_pk_mul_f32 v[68:69], v[166:167], v[28:29] op_sel_hi:[0,1]
	v_pk_fma_f32 v[68:69], v[174:175], v[202:203], v[68:69] op_sel_hi:[0,1,1] neg_lo:[0,0,1] neg_hi:[0,0,1]
	v_pk_fma_f32 v[62:63], v[62:63], v[154:155], v[68:69] op_sel_hi:[1,0,1]
	v_pk_mul_f32 v[68:69], v[166:167], v[28:29] op_sel:[1,0]
	v_pk_fma_f32 v[30:31], v[178:179], v[2:3], 0 op_sel_hi:[0,1,0]
	v_pk_fma_f32 v[68:69], v[174:175], v[202:203], v[68:69] op_sel:[1,0,0] neg_lo:[0,0,1] neg_hi:[0,0,1]
	v_pk_fma_f32 v[30:31], v[180:181], v[34:35], v[30:31] op_sel_hi:[0,1,1]
	v_pk_fma_f32 v[60:61], v[60:61], v[154:155], v[68:69] op_sel:[0,1,0]
	v_pk_fma_f32 v[70:71], v[198:199], v[60:61], v[66:67] op_sel:[1,0,0]
	v_pk_mul_f32 v[66:67], v[168:169], v[28:29] op_sel_hi:[0,1]
	v_pk_fma_f32 v[66:67], v[176:177], v[202:203], v[66:67] op_sel_hi:[0,1,1] neg_lo:[0,0,1] neg_hi:[0,0,1]
	v_pk_mul_f32 v[28:29], v[168:169], v[28:29] op_sel:[1,0]
	v_pk_fma_f32 v[30:31], v[198:199], v[62:63], v[30:31] op_sel_hi:[0,1,1]
	v_pk_fma_f32 v[66:67], v[46:47], v[156:157], v[66:67] op_sel_hi:[1,0,1]
	v_pk_fma_f32 v[28:29], v[176:177], v[202:203], v[28:29] op_sel:[1,0,0] neg_lo:[0,0,1] neg_hi:[0,0,1]
	v_pk_fma_f32 v[68:69], v[44:45], v[156:157], v[28:29] op_sel:[0,1,0]
	v_pk_fma_f32 v[28:29], v[200:201], v[66:67], v[30:31] op_sel_hi:[0,1,1]
	v_pk_fma_f32 v[30:31], v[200:201], v[68:69], v[70:71] op_sel:[1,0,0]
	v_pk_add_f32 v[28:29], v[28:29], v[30:31]
	v_add_u32_e32 v153, s20, v99
	s_nop 0
	v_mov_b32_dpp v30, v28 quad_perm:[1,0,3,2] row_mask:0xf bank_mask:0xf bound_ctrl:1
	v_mov_b32_dpp v31, v29 quad_perm:[1,0,3,2] row_mask:0xf bank_mask:0xf bound_ctrl:1
	v_pk_add_f32 v[28:29], v[28:29], v[30:31]
	s_nop 1
	v_mov_b32_dpp v30, v28 quad_perm:[2,3,0,1] row_mask:0xf bank_mask:0xf bound_ctrl:1
	v_mov_b32_dpp v31, v29 quad_perm:[2,3,0,1] row_mask:0xf bank_mask:0xf bound_ctrl:1
	v_pk_add_f32 v[28:29], v[28:29], v[30:31]
	s_nop 1
	v_mov_b32_dpp v30, v28 row_half_mirror row_mask:0xf bank_mask:0xf bound_ctrl:1
	v_mov_b32_dpp v31, v29 row_half_mirror row_mask:0xf bank_mask:0xf bound_ctrl:1
	s_and_saveexec_b64 s[20:21], s[14:15]
	v_pk_add_f32 v[28:29], v[28:29], v[30:31]
	ds_write_b64 v153, v[28:29] offset:50688
	s_or_b64 exec, exec, s[20:21]
	s_waitcnt lgkmcnt(1)
	v_pk_mul_f32 v[202:203], v[42:43], v[34:35] op_sel_hi:[0,1]
	v_pk_fma_f32 v[202:203], v[40:41], v[2:3], v[202:203] op_sel_hi:[0,1,1]
	v_pk_mul_f32 v[42:43], v[42:43], v[64:65] op_sel:[1,0]
	v_pk_fma_f32 v[40:41], v[40:41], v[32:33], v[42:43] op_sel:[1,0,0]
	s_waitcnt lgkmcnt(0)
	v_pk_fma_f32 v[42:43], v[36:37], v[62:63], v[202:203] op_sel_hi:[0,1,1]
	v_pk_fma_f32 v[36:37], v[36:37], v[60:61], v[40:41] op_sel:[1,0,0]
	v_pk_fma_f32 v[40:41], v[38:39], v[66:67], v[42:43] op_sel_hi:[0,1,1]
	v_pk_fma_f32 v[36:37], v[38:39], v[68:69], v[36:37] op_sel:[1,0,0]
	v_pk_add_f32 v[36:37], v[40:41], v[36:37]
	ds_read_b128 v[70:73], v152 offset:5888
	ds_read_b128 v[154:157], v152 offset:5904
	ds_read_b128 v[158:161], v152 offset:9984
	ds_read_b128 v[166:169], v152 offset:10000
	ds_read_b128 v[170:173], v152 offset:14080
	ds_read_b128 v[174:177], v152 offset:14096
	ds_read_b128 v[178:181], v152 offset:18176
	ds_read_b128 v[198:201], v152 offset:18192
	ds_read_b64 v[74:75], v1 offset:22272
	ds_read_b128 v[44:47], v151 offset:2048
	ds_read_b128 v[28:31], v151 offset:2064
	v_mov_b32_dpp v38, v36 quad_perm:[1,0,3,2] row_mask:0xf bank_mask:0xf bound_ctrl:1
	v_mov_b32_dpp v39, v37 quad_perm:[1,0,3,2] row_mask:0xf bank_mask:0xf bound_ctrl:1
	v_pk_add_f32 v[36:37], v[36:37], v[38:39]
	s_nop 1
	v_mov_b32_dpp v38, v36 quad_perm:[2,3,0,1] row_mask:0xf bank_mask:0xf bound_ctrl:1
	v_mov_b32_dpp v39, v37 quad_perm:[2,3,0,1] row_mask:0xf bank_mask:0xf bound_ctrl:1
	v_pk_add_f32 v[36:37], v[36:37], v[38:39]
	s_nop 1
	v_mov_b32_dpp v38, v36 row_half_mirror row_mask:0xf bank_mask:0xf bound_ctrl:1
	v_mov_b32_dpp v39, v37 row_half_mirror row_mask:0xf bank_mask:0xf bound_ctrl:1
	v_pk_add_f32 v[40:41], v[36:37], v[38:39]
	s_waitcnt lgkmcnt(8)
	v_pk_mul_f32 v[36:37], v[158:159], v[40:41] op_sel_hi:[0,1]
	s_waitcnt lgkmcnt(2)
	v_pk_fma_f32 v[36:37], v[170:171], v[74:75], v[36:37] op_sel_hi:[0,1,1] neg_lo:[0,0,1] neg_hi:[0,0,1]
	v_pk_fma_f32 v[2:3], v[2:3], v[70:71], v[36:37] op_sel_hi:[1,0,1]
	v_pk_mul_f32 v[36:37], v[158:159], v[40:41] op_sel:[1,0]
	v_pk_mul_f32 v[38:39], v[160:161], v[40:41] op_sel_hi:[0,1]
	v_pk_fma_f32 v[36:37], v[170:171], v[74:75], v[36:37] op_sel:[1,0,0] neg_lo:[0,0,1] neg_hi:[0,0,1]
	v_pk_fma_f32 v[38:39], v[172:173], v[74:75], v[38:39] op_sel_hi:[0,1,1] neg_lo:[0,0,1] neg_hi:[0,0,1]
	v_pk_fma_f32 v[36:37], v[32:33], v[70:71], v[36:37] op_sel:[0,1,0]
	v_pk_fma_f32 v[38:39], v[34:35], v[72:73], v[38:39] op_sel_hi:[1,0,1]
	v_pk_mul_f32 v[70:71], v[160:161], v[40:41] op_sel:[1,0]
	v_pk_fma_f32 v[70:71], v[172:173], v[74:75], v[70:71] op_sel:[1,0,0] neg_lo:[0,0,1] neg_hi:[0,0,1]
	v_pk_fma_f32 v[42:43], v[178:179], v[36:37], 0 op_sel:[1,0,0] op_sel_hi:[1,1,0]
	v_pk_fma_f32 v[64:65], v[64:65], v[72:73], v[70:71] op_sel:[0,1,0]
	v_pk_fma_f32 v[34:35], v[180:181], v[64:65], v[42:43] op_sel:[1,0,0]
	v_pk_mul_f32 v[42:43], v[166:167], v[40:41] op_sel_hi:[0,1]
	v_pk_fma_f32 v[42:43], v[174:175], v[74:75], v[42:43] op_sel_hi:[0,1,1] neg_lo:[0,0,1] neg_hi:[0,0,1]
	v_pk_fma_f32 v[62:63], v[62:63], v[154:155], v[42:43] op_sel_hi:[1,0,1]
	v_pk_mul_f32 v[42:43], v[166:167], v[40:41] op_sel:[1,0]
	v_pk_fma_f32 v[42:43], v[174:175], v[74:75], v[42:43] op_sel:[1,0,0] neg_lo:[0,0,1] neg_hi:[0,0,1]
	v_pk_fma_f32 v[32:33], v[178:179], v[2:3], 0 op_sel_hi:[0,1,0]
	v_pk_fma_f32 v[60:61], v[60:61], v[154:155], v[42:43] op_sel:[0,1,0]
	v_pk_mul_f32 v[42:43], v[168:169], v[40:41] op_sel_hi:[0,1]
	v_pk_fma_f32 v[42:43], v[176:177], v[74:75], v[42:43] op_sel_hi:[0,1,1] neg_lo:[0,0,1] neg_hi:[0,0,1]
	v_pk_mul_f32 v[40:41], v[168:169], v[40:41] op_sel:[1,0]
	v_pk_fma_f32 v[32:33], v[180:181], v[38:39], v[32:33] op_sel_hi:[0,1,1]
	v_pk_fma_f32 v[66:67], v[66:67], v[156:157], v[42:43] op_sel_hi:[1,0,1]
	v_pk_fma_f32 v[40:41], v[176:177], v[74:75], v[40:41] op_sel:[1,0,0] neg_lo:[0,0,1] neg_hi:[0,0,1]
	v_pk_fma_f32 v[32:33], v[198:199], v[62:63], v[32:33] op_sel_hi:[0,1,1]
	v_pk_fma_f32 v[34:35], v[198:199], v[60:61], v[34:35] op_sel:[1,0,0]
	v_pk_fma_f32 v[68:69], v[68:69], v[156:157], v[40:41] op_sel:[0,1,0]
	v_pk_fma_f32 v[32:33], v[200:201], v[66:67], v[32:33] op_sel_hi:[0,1,1]
	v_pk_fma_f32 v[34:35], v[200:201], v[68:69], v[34:35] op_sel:[1,0,0]
	v_pk_add_f32 v[32:33], v[32:33], v[34:35]
	s_nop 1
	v_mov_b32_dpp v34, v32 quad_perm:[1,0,3,2] row_mask:0xf bank_mask:0xf bound_ctrl:1
	v_mov_b32_dpp v35, v33 quad_perm:[1,0,3,2] row_mask:0xf bank_mask:0xf bound_ctrl:1
	v_pk_add_f32 v[32:33], v[32:33], v[34:35]
	s_nop 1
	v_mov_b32_dpp v34, v32 quad_perm:[2,3,0,1] row_mask:0xf bank_mask:0xf bound_ctrl:1
	v_mov_b32_dpp v35, v33 quad_perm:[2,3,0,1] row_mask:0xf bank_mask:0xf bound_ctrl:1
	v_pk_add_f32 v[32:33], v[32:33], v[34:35]
	s_nop 1
	v_mov_b32_dpp v34, v32 row_half_mirror row_mask:0xf bank_mask:0xf bound_ctrl:1
	v_mov_b32_dpp v35, v33 row_half_mirror row_mask:0xf bank_mask:0xf bound_ctrl:1
	s_and_saveexec_b64 s[20:21], s[14:15]
	v_pk_add_f32 v[32:33], v[32:33], v[34:35]
	ds_write_b64 v153, v[32:33] offset:50944
	s_or_b64 exec, exec, s[20:21]
	s_waitcnt lgkmcnt(1)
	v_pk_mul_f32 v[202:203], v[46:47], v[38:39] op_sel_hi:[0,1]
	v_pk_fma_f32 v[202:203], v[44:45], v[2:3], v[202:203] op_sel_hi:[0,1,1]
	v_pk_mul_f32 v[46:47], v[46:47], v[64:65] op_sel:[1,0]
	v_pk_fma_f32 v[44:45], v[44:45], v[36:37], v[46:47] op_sel:[1,0,0]
	s_waitcnt lgkmcnt(0)
	v_pk_fma_f32 v[46:47], v[28:29], v[62:63], v[202:203] op_sel_hi:[0,1,1]
	v_pk_fma_f32 v[28:29], v[28:29], v[60:61], v[44:45] op_sel:[1,0,0]
	v_pk_fma_f32 v[44:45], v[30:31], v[66:67], v[46:47] op_sel_hi:[0,1,1]
	v_pk_fma_f32 v[28:29], v[30:31], v[68:69], v[28:29] op_sel:[1,0,0]
	v_pk_add_f32 v[28:29], v[44:45], v[28:29]
	ds_read_b128 v[70:73], v152 offset:6144
	ds_read_b128 v[154:157], v152 offset:6160
	ds_read_b128 v[158:161], v152 offset:10240
	ds_read_b128 v[166:169], v152 offset:10256
	ds_read_b128 v[170:173], v152 offset:14336
	ds_read_b128 v[174:177], v152 offset:14352
	ds_read_b128 v[178:181], v152 offset:18432
	ds_read_b128 v[198:201], v152 offset:18448
	ds_read_b64 v[74:75], v1 offset:22528
	ds_read_b128 v[40:43], v151 offset:2304
	ds_read_b128 v[32:35], v151 offset:2320
	v_mov_b32_dpp v30, v28 quad_perm:[1,0,3,2] row_mask:0xf bank_mask:0xf bound_ctrl:1
	v_mov_b32_dpp v31, v29 quad_perm:[1,0,3,2] row_mask:0xf bank_mask:0xf bound_ctrl:1
	v_pk_add_f32 v[28:29], v[28:29], v[30:31]
	s_nop 1
	v_mov_b32_dpp v30, v28 quad_perm:[2,3,0,1] row_mask:0xf bank_mask:0xf bound_ctrl:1
	v_mov_b32_dpp v31, v29 quad_perm:[2,3,0,1] row_mask:0xf bank_mask:0xf bound_ctrl:1
	v_pk_add_f32 v[28:29], v[28:29], v[30:31]
	s_nop 1
	v_mov_b32_dpp v30, v28 row_half_mirror row_mask:0xf bank_mask:0xf bound_ctrl:1
	v_mov_b32_dpp v31, v29 row_half_mirror row_mask:0xf bank_mask:0xf bound_ctrl:1
	v_pk_add_f32 v[44:45], v[28:29], v[30:31]
	s_waitcnt lgkmcnt(8)
	v_pk_mul_f32 v[28:29], v[158:159], v[44:45] op_sel_hi:[0,1]
	s_waitcnt lgkmcnt(2)
	v_pk_fma_f32 v[28:29], v[170:171], v[74:75], v[28:29] op_sel_hi:[0,1,1] neg_lo:[0,0,1] neg_hi:[0,0,1]
	v_pk_fma_f32 v[2:3], v[2:3], v[70:71], v[28:29] op_sel_hi:[1,0,1]
	v_pk_mul_f32 v[28:29], v[158:159], v[44:45] op_sel:[1,0]
	v_pk_mul_f32 v[30:31], v[160:161], v[44:45] op_sel_hi:[0,1]
	v_pk_fma_f32 v[28:29], v[170:171], v[74:75], v[28:29] op_sel:[1,0,0] neg_lo:[0,0,1] neg_hi:[0,0,1]
	v_pk_fma_f32 v[30:31], v[172:173], v[74:75], v[30:31] op_sel_hi:[0,1,1] neg_lo:[0,0,1] neg_hi:[0,0,1]
	v_pk_fma_f32 v[28:29], v[36:37], v[70:71], v[28:29] op_sel:[0,1,0]
	v_pk_fma_f32 v[30:31], v[38:39], v[72:73], v[30:31] op_sel_hi:[1,0,1]
	v_pk_mul_f32 v[70:71], v[160:161], v[44:45] op_sel:[1,0]
	v_pk_fma_f32 v[70:71], v[172:173], v[74:75], v[70:71] op_sel:[1,0,0] neg_lo:[0,0,1] neg_hi:[0,0,1]
	v_pk_fma_f32 v[46:47], v[178:179], v[28:29], 0 op_sel:[1,0,0] op_sel_hi:[1,1,0]
	v_pk_fma_f32 v[64:65], v[64:65], v[72:73], v[70:71] op_sel:[0,1,0]
	v_pk_fma_f32 v[38:39], v[180:181], v[64:65], v[46:47] op_sel:[1,0,0]
	v_pk_mul_f32 v[46:47], v[166:167], v[44:45] op_sel_hi:[0,1]
	v_pk_fma_f32 v[46:47], v[174:175], v[74:75], v[46:47] op_sel_hi:[0,1,1] neg_lo:[0,0,1] neg_hi:[0,0,1]
	v_pk_fma_f32 v[62:63], v[62:63], v[154:155], v[46:47] op_sel_hi:[1,0,1]
	v_pk_mul_f32 v[46:47], v[166:167], v[44:45] op_sel:[1,0]
	v_pk_fma_f32 v[46:47], v[174:175], v[74:75], v[46:47] op_sel:[1,0,0] neg_lo:[0,0,1] neg_hi:[0,0,1]
	v_pk_fma_f32 v[36:37], v[178:179], v[2:3], 0 op_sel_hi:[0,1,0]
	v_pk_fma_f32 v[60:61], v[60:61], v[154:155], v[46:47] op_sel:[0,1,0]
	v_pk_mul_f32 v[46:47], v[168:169], v[44:45] op_sel_hi:[0,1]
	v_pk_fma_f32 v[46:47], v[176:177], v[74:75], v[46:47] op_sel_hi:[0,1,1] neg_lo:[0,0,1] neg_hi:[0,0,1]
	v_pk_mul_f32 v[44:45], v[168:169], v[44:45] op_sel:[1,0]
	v_pk_fma_f32 v[36:37], v[180:181], v[30:31], v[36:37] op_sel_hi:[0,1,1]
	v_pk_fma_f32 v[66:67], v[66:67], v[156:157], v[46:47] op_sel_hi:[1,0,1]
	v_pk_fma_f32 v[44:45], v[176:177], v[74:75], v[44:45] op_sel:[1,0,0] neg_lo:[0,0,1] neg_hi:[0,0,1]
	v_pk_fma_f32 v[36:37], v[198:199], v[62:63], v[36:37] op_sel_hi:[0,1,1]
	v_pk_fma_f32 v[38:39], v[198:199], v[60:61], v[38:39] op_sel:[1,0,0]
	v_pk_fma_f32 v[68:69], v[68:69], v[156:157], v[44:45] op_sel:[0,1,0]
	v_pk_fma_f32 v[36:37], v[200:201], v[66:67], v[36:37] op_sel_hi:[0,1,1]
	v_pk_fma_f32 v[38:39], v[200:201], v[68:69], v[38:39] op_sel:[1,0,0]
	v_pk_add_f32 v[36:37], v[36:37], v[38:39]
	s_nop 1
	v_mov_b32_dpp v38, v36 quad_perm:[1,0,3,2] row_mask:0xf bank_mask:0xf bound_ctrl:1
	v_mov_b32_dpp v39, v37 quad_perm:[1,0,3,2] row_mask:0xf bank_mask:0xf bound_ctrl:1
	v_pk_add_f32 v[36:37], v[36:37], v[38:39]
	s_nop 1
	v_mov_b32_dpp v38, v36 quad_perm:[2,3,0,1] row_mask:0xf bank_mask:0xf bound_ctrl:1
	v_mov_b32_dpp v39, v37 quad_perm:[2,3,0,1] row_mask:0xf bank_mask:0xf bound_ctrl:1
	v_pk_add_f32 v[36:37], v[36:37], v[38:39]
	s_nop 1
	v_mov_b32_dpp v38, v36 row_half_mirror row_mask:0xf bank_mask:0xf bound_ctrl:1
	v_mov_b32_dpp v39, v37 row_half_mirror row_mask:0xf bank_mask:0xf bound_ctrl:1
	s_and_saveexec_b64 s[20:21], s[14:15]
	v_pk_add_f32 v[36:37], v[36:37], v[38:39]
	ds_write_b64 v153, v[36:37] offset:51200
	s_or_b64 exec, exec, s[20:21]
	s_waitcnt lgkmcnt(1)
	v_pk_mul_f32 v[202:203], v[42:43], v[30:31] op_sel_hi:[0,1]
	v_pk_fma_f32 v[202:203], v[40:41], v[2:3], v[202:203] op_sel_hi:[0,1,1]
	v_pk_mul_f32 v[42:43], v[42:43], v[64:65] op_sel:[1,0]
	v_pk_fma_f32 v[40:41], v[40:41], v[28:29], v[42:43] op_sel:[1,0,0]
	s_waitcnt lgkmcnt(0)
	v_pk_fma_f32 v[42:43], v[32:33], v[62:63], v[202:203] op_sel_hi:[0,1,1]
	v_pk_fma_f32 v[32:33], v[32:33], v[60:61], v[40:41] op_sel:[1,0,0]
	v_pk_fma_f32 v[40:41], v[34:35], v[66:67], v[42:43] op_sel_hi:[0,1,1]
	v_pk_fma_f32 v[32:33], v[34:35], v[68:69], v[32:33] op_sel:[1,0,0]
	v_pk_add_f32 v[32:33], v[40:41], v[32:33]
	ds_read_b128 v[70:73], v152 offset:6400
	ds_read_b128 v[154:157], v152 offset:6416
	ds_read_b128 v[158:161], v152 offset:10496
	ds_read_b128 v[166:169], v152 offset:10512
	ds_read_b128 v[170:173], v152 offset:14592
	ds_read_b128 v[174:177], v152 offset:14608
	ds_read_b128 v[178:181], v152 offset:18688
	ds_read_b128 v[198:201], v152 offset:18704
	ds_read_b64 v[74:75], v1 offset:22784
	ds_read_b128 v[44:47], v151 offset:2560
	ds_read_b128 v[36:39], v151 offset:2576
	v_mov_b32_dpp v34, v32 quad_perm:[1,0,3,2] row_mask:0xf bank_mask:0xf bound_ctrl:1
	v_mov_b32_dpp v35, v33 quad_perm:[1,0,3,2] row_mask:0xf bank_mask:0xf bound_ctrl:1
	v_pk_add_f32 v[32:33], v[32:33], v[34:35]
	s_nop 1
	v_mov_b32_dpp v34, v32 quad_perm:[2,3,0,1] row_mask:0xf bank_mask:0xf bound_ctrl:1
	v_mov_b32_dpp v35, v33 quad_perm:[2,3,0,1] row_mask:0xf bank_mask:0xf bound_ctrl:1
	v_pk_add_f32 v[32:33], v[32:33], v[34:35]
	s_nop 1
	v_mov_b32_dpp v34, v32 row_half_mirror row_mask:0xf bank_mask:0xf bound_ctrl:1
	v_mov_b32_dpp v35, v33 row_half_mirror row_mask:0xf bank_mask:0xf bound_ctrl:1
	v_pk_add_f32 v[32:33], v[32:33], v[34:35]
	s_waitcnt lgkmcnt(8)
	v_pk_mul_f32 v[34:35], v[158:159], v[32:33] op_sel_hi:[0,1]
	s_waitcnt lgkmcnt(2)
	v_pk_fma_f32 v[34:35], v[170:171], v[74:75], v[34:35] op_sel_hi:[0,1,1] neg_lo:[0,0,1] neg_hi:[0,0,1]
	v_pk_fma_f32 v[2:3], v[2:3], v[70:71], v[34:35] op_sel_hi:[1,0,1]
	v_pk_mul_f32 v[34:35], v[158:159], v[32:33] op_sel:[1,0]
	v_pk_mul_f32 v[42:43], v[160:161], v[32:33] op_sel_hi:[0,1]
	v_pk_fma_f32 v[34:35], v[170:171], v[74:75], v[34:35] op_sel:[1,0,0] neg_lo:[0,0,1] neg_hi:[0,0,1]
	v_pk_fma_f32 v[42:43], v[172:173], v[74:75], v[42:43] op_sel_hi:[0,1,1] neg_lo:[0,0,1] neg_hi:[0,0,1]
	v_pk_fma_f32 v[40:41], v[28:29], v[70:71], v[34:35] op_sel:[0,1,0]
	v_pk_fma_f32 v[42:43], v[30:31], v[72:73], v[42:43] op_sel_hi:[1,0,1]
	v_pk_mul_f32 v[70:71], v[160:161], v[32:33] op_sel:[1,0]
	v_pk_fma_f32 v[70:71], v[172:173], v[74:75], v[70:71] op_sel:[1,0,0] neg_lo:[0,0,1] neg_hi:[0,0,1]
	v_pk_fma_f32 v[34:35], v[178:179], v[40:41], 0 op_sel:[1,0,0] op_sel_hi:[1,1,0]
	v_pk_fma_f32 v[64:65], v[64:65], v[72:73], v[70:71] op_sel:[0,1,0]
	v_pk_fma_f32 v[30:31], v[180:181], v[64:65], v[34:35] op_sel:[1,0,0]
	v_pk_mul_f32 v[34:35], v[166:167], v[32:33] op_sel_hi:[0,1]
	v_pk_fma_f32 v[34:35], v[174:175], v[74:75], v[34:35] op_sel_hi:[0,1,1] neg_lo:[0,0,1] neg_hi:[0,0,1]
	v_pk_fma_f32 v[62:63], v[62:63], v[154:155], v[34:35] op_sel_hi:[1,0,1]
	v_pk_mul_f32 v[34:35], v[166:167], v[32:33] op_sel:[1,0]
	v_pk_fma_f32 v[28:29], v[178:179], v[2:3], 0 op_sel_hi:[0,1,0]
	v_pk_fma_f32 v[34:35], v[174:175], v[74:75], v[34:35] op_sel:[1,0,0] neg_lo:[0,0,1] neg_hi:[0,0,1]
	v_pk_fma_f32 v[60:61], v[60:61], v[154:155], v[34:35] op_sel:[0,1,0]
	v_pk_mul_f32 v[34:35], v[168:169], v[32:33] op_sel_hi:[0,1]
	v_pk_fma_f32 v[34:35], v[176:177], v[74:75], v[34:35] op_sel_hi:[0,1,1] neg_lo:[0,0,1] neg_hi:[0,0,1]
	v_pk_fma_f32 v[72:73], v[66:67], v[156:157], v[34:35] op_sel_hi:[1,0,1]
	v_pk_mul_f32 v[32:33], v[168:169], v[32:33] op_sel:[1,0]
	v_pk_fma_f32 v[28:29], v[180:181], v[42:43], v[28:29] op_sel_hi:[0,1,1]
	v_pk_fma_f32 v[32:33], v[176:177], v[74:75], v[32:33] op_sel:[1,0,0] neg_lo:[0,0,1] neg_hi:[0,0,1]
	v_pk_fma_f32 v[28:29], v[198:199], v[62:63], v[28:29] op_sel_hi:[0,1,1]
	v_pk_fma_f32 v[30:31], v[198:199], v[60:61], v[30:31] op_sel:[1,0,0]
	v_pk_fma_f32 v[74:75], v[68:69], v[156:157], v[32:33] op_sel:[0,1,0]
	v_pk_fma_f32 v[28:29], v[200:201], v[72:73], v[28:29] op_sel_hi:[0,1,1]
	v_pk_fma_f32 v[30:31], v[200:201], v[74:75], v[30:31] op_sel:[1,0,0]
	v_pk_add_f32 v[28:29], v[28:29], v[30:31]
	s_nop 1
	v_mov_b32_dpp v30, v28 quad_perm:[1,0,3,2] row_mask:0xf bank_mask:0xf bound_ctrl:1
	v_mov_b32_dpp v31, v29 quad_perm:[1,0,3,2] row_mask:0xf bank_mask:0xf bound_ctrl:1
	v_pk_add_f32 v[28:29], v[28:29], v[30:31]
	s_nop 1
	v_mov_b32_dpp v30, v28 quad_perm:[2,3,0,1] row_mask:0xf bank_mask:0xf bound_ctrl:1
	v_mov_b32_dpp v31, v29 quad_perm:[2,3,0,1] row_mask:0xf bank_mask:0xf bound_ctrl:1
	v_pk_add_f32 v[28:29], v[28:29], v[30:31]
	s_nop 1
	v_mov_b32_dpp v30, v28 row_half_mirror row_mask:0xf bank_mask:0xf bound_ctrl:1
	v_mov_b32_dpp v31, v29 row_half_mirror row_mask:0xf bank_mask:0xf bound_ctrl:1
	s_and_saveexec_b64 s[20:21], s[14:15]
	v_pk_add_f32 v[28:29], v[28:29], v[30:31]
	ds_write_b64 v153, v[28:29] offset:51456
	s_or_b64 exec, exec, s[20:21]
	s_waitcnt lgkmcnt(1)
	v_pk_mul_f32 v[66:67], v[46:47], v[42:43] op_sel_hi:[0,1]
	v_pk_fma_f32 v[66:67], v[44:45], v[2:3], v[66:67] op_sel_hi:[0,1,1]
	v_pk_mul_f32 v[46:47], v[46:47], v[64:65] op_sel:[1,0]
	v_pk_fma_f32 v[44:45], v[44:45], v[40:41], v[46:47] op_sel:[1,0,0]
	s_waitcnt lgkmcnt(0)
	v_pk_fma_f32 v[46:47], v[36:37], v[62:63], v[66:67] op_sel_hi:[0,1,1]
	v_pk_fma_f32 v[36:37], v[36:37], v[60:61], v[44:45] op_sel:[1,0,0]
	v_pk_fma_f32 v[44:45], v[38:39], v[72:73], v[46:47] op_sel_hi:[0,1,1]
	v_pk_fma_f32 v[36:37], v[38:39], v[74:75], v[36:37] op_sel:[1,0,0]
	v_pk_add_f32 v[36:37], v[44:45], v[36:37]
	ds_read_b128 v[154:157], v152 offset:6656
	ds_read_b128 v[158:161], v152 offset:6672
	ds_read_b128 v[166:169], v152 offset:10752
	ds_read_b128 v[170:173], v152 offset:10768
	ds_read_b128 v[174:177], v152 offset:14848
	ds_read_b128 v[178:181], v152 offset:14864
	ds_read_b128 v[198:201], v152 offset:18944
	ds_read_b128 v[202:205], v152 offset:18960
	ds_read_b64 v[206:207], v1 offset:23040
	ds_read_b128 v[32:35], v151 offset:2816
	ds_read_b128 v[28:31], v151 offset:2832
	v_mov_b32_dpp v38, v36 quad_perm:[1,0,3,2] row_mask:0xf bank_mask:0xf bound_ctrl:1
	v_mov_b32_dpp v39, v37 quad_perm:[1,0,3,2] row_mask:0xf bank_mask:0xf bound_ctrl:1
	v_pk_add_f32 v[36:37], v[36:37], v[38:39]
	s_waitcnt lgkmcnt(6)
	v_mov_b32_dpp v38, v36 quad_perm:[2,3,0,1] row_mask:0xf bank_mask:0xf bound_ctrl:1
	v_mov_b32_dpp v39, v37 quad_perm:[2,3,0,1] row_mask:0xf bank_mask:0xf bound_ctrl:1
	v_pk_add_f32 v[36:37], v[36:37], v[38:39]
	s_nop 1
	v_mov_b32_dpp v38, v36 row_half_mirror row_mask:0xf bank_mask:0xf bound_ctrl:1
	v_mov_b32_dpp v39, v37 row_half_mirror row_mask:0xf bank_mask:0xf bound_ctrl:1
	v_pk_add_f32 v[36:37], v[36:37], v[38:39]
	s_nop 0
	v_pk_mul_f32 v[38:39], v[166:167], v[36:37] op_sel_hi:[0,1]
	s_waitcnt lgkmcnt(2)
	v_pk_fma_f32 v[38:39], v[174:175], v[206:207], v[38:39] op_sel_hi:[0,1,1] neg_lo:[0,0,1] neg_hi:[0,0,1]
	v_pk_fma_f32 v[70:71], v[2:3], v[154:155], v[38:39] op_sel_hi:[1,0,1]
	v_pk_mul_f32 v[2:3], v[166:167], v[36:37] op_sel:[1,0]
	s_nop 0
	v_pk_fma_f32 v[2:3], v[174:175], v[206:207], v[2:3] op_sel:[1,0,0] neg_lo:[0,0,1] neg_hi:[0,0,1]
	s_nop 0
	v_pk_fma_f32 v[68:69], v[40:41], v[154:155], v[2:3] op_sel:[0,1,0]
	v_pk_mul_f32 v[40:41], v[168:169], v[36:37] op_sel_hi:[0,1]
	v_pk_fma_f32 v[40:41], v[176:177], v[206:207], v[40:41] op_sel_hi:[0,1,1] neg_lo:[0,0,1] neg_hi:[0,0,1]
	v_pk_fma_f32 v[66:67], v[42:43], v[156:157], v[40:41] op_sel_hi:[1,0,1]
	v_pk_mul_f32 v[42:43], v[168:169], v[36:37] op_sel:[1,0]
	v_pk_fma_f32 v[42:43], v[176:177], v[206:207], v[42:43] op_sel:[1,0,0] neg_lo:[0,0,1] neg_hi:[0,0,1]
	v_pk_fma_f32 v[38:39], v[198:199], v[68:69], 0 op_sel:[1,0,0] op_sel_hi:[1,1,0]
	v_pk_fma_f32 v[64:65], v[64:65], v[156:157], v[42:43] op_sel:[0,1,0]
	v_pk_fma_f32 v[38:39], v[200:201], v[64:65], v[38:39] op_sel:[1,0,0]
	v_pk_mul_f32 v[40:41], v[170:171], v[36:37] op_sel_hi:[0,1]
	v_pk_fma_f32 v[40:41], v[178:179], v[206:207], v[40:41] op_sel_hi:[0,1,1] neg_lo:[0,0,1] neg_hi:[0,0,1]
	v_pk_fma_f32 v[62:63], v[62:63], v[158:159], v[40:41] op_sel_hi:[1,0,1]
	v_pk_mul_f32 v[40:41], v[170:171], v[36:37] op_sel:[1,0]
	v_mov_b32_e32 v42, v173
	v_pk_fma_f32 v[40:41], v[178:179], v[206:207], v[40:41] op_sel:[1,0,0] neg_lo:[0,0,1] neg_hi:[0,0,1]
	v_pk_fma_f32 v[2:3], v[198:199], v[70:71], 0 op_sel_hi:[0,1,0]
	v_pk_fma_f32 v[60:61], v[60:61], v[158:159], v[40:41] op_sel:[0,1,0]
	v_pk_mul_f32 v[40:41], v[172:173], v[36:37] op_sel_hi:[0,1]
	v_pk_fma_f32 v[40:41], v[180:181], v[206:207], v[40:41] op_sel_hi:[0,1,1] neg_lo:[0,0,1] neg_hi:[0,0,1]
	v_pk_mul_f32 v[36:37], v[42:43], v[36:37] op_sel_hi:[0,1]
	v_pk_fma_f32 v[2:3], v[200:201], v[66:67], v[2:3] op_sel_hi:[0,1,1]
	v_pk_fma_f32 v[46:47], v[72:73], v[160:161], v[40:41] op_sel_hi:[1,0,1]
	v_mov_b32_e32 v40, v161
	v_pk_fma_f32 v[36:37], v[180:181], v[206:207], v[36:37] op_sel:[1,0,0] neg_lo:[0,0,1] neg_hi:[0,0,1]
	v_pk_fma_f32 v[2:3], v[202:203], v[62:63], v[2:3] op_sel_hi:[0,1,1]
	v_pk_fma_f32 v[38:39], v[202:203], v[60:61], v[38:39] op_sel:[1,0,0]
	v_pk_fma_f32 v[44:45], v[74:75], v[40:41], v[36:37] op_sel_hi:[1,0,1]
	v_pk_fma_f32 v[2:3], v[204:205], v[46:47], v[2:3] op_sel_hi:[0,1,1]
	v_pk_fma_f32 v[36:37], v[204:205], v[44:45], v[38:39] op_sel:[1,0,0]
	v_pk_add_f32 v[2:3], v[2:3], v[36:37]
	s_nop 1
	v_mov_b32_dpp v36, v2 quad_perm:[1,0,3,2] row_mask:0xf bank_mask:0xf bound_ctrl:1
	v_mov_b32_dpp v37, v3 quad_perm:[1,0,3,2] row_mask:0xf bank_mask:0xf bound_ctrl:1
	v_pk_add_f32 v[2:3], v[2:3], v[36:37]
	s_nop 1
	v_mov_b32_dpp v36, v2 quad_perm:[2,3,0,1] row_mask:0xf bank_mask:0xf bound_ctrl:1
	v_mov_b32_dpp v37, v3 quad_perm:[2,3,0,1] row_mask:0xf bank_mask:0xf bound_ctrl:1
	v_pk_add_f32 v[2:3], v[2:3], v[36:37]
	s_nop 1
	v_mov_b32_dpp v36, v2 row_half_mirror row_mask:0xf bank_mask:0xf bound_ctrl:1
	v_mov_b32_dpp v37, v3 row_half_mirror row_mask:0xf bank_mask:0xf bound_ctrl:1
	s_and_saveexec_b64 s[20:21], s[14:15]
	v_pk_add_f32 v[2:3], v[2:3], v[36:37]
	ds_write_b64 v153, v[2:3] offset:51712
	s_or_b64 exec, exec, s[20:21]

.LBB0_635:
	s_andn2_saveexec_b64 s[0:1], s[0:1]
	s_cbranch_execz .LBB0_576
	v_pk_mul_f32 v[2:3], v[66:67], v[34:35] op_sel_hi:[1,0]
	v_pk_fma_f32 v[2:3], v[70:71], v[32:33], v[2:3] op_sel_hi:[1,0,1]
	v_pk_mul_f32 v[34:35], v[64:65], v[34:35] op_sel:[0,1]
	v_pk_fma_f32 v[2:3], v[62:63], v[28:29], v[2:3] op_sel_hi:[1,0,1]
	v_pk_fma_f32 v[32:33], v[68:69], v[32:33], v[34:35] op_sel:[0,1,0]
	v_pk_fma_f32 v[2:3], v[46:47], v[30:31], v[2:3] op_sel_hi:[1,0,1]
	v_pk_fma_f32 v[28:29], v[60:61], v[28:29], v[32:33] op_sel:[0,1,0]
	v_pk_fma_f32 v[28:29], v[44:45], v[30:31], v[28:29] op_sel:[0,1,0]
	s_and_b32 s20, s25, 1
	v_pk_add_f32 v[2:3], v[2:3], v[28:29]
	s_mul_i32 s21, s20, 0x6000
	s_add_i32 s21, s21, 0
	v_mov_b32_dpp v28, v2 quad_perm:[1,0,3,2] row_mask:0xf bank_mask:0xf bound_ctrl:1
	v_mov_b32_dpp v29, v3 quad_perm:[1,0,3,2] row_mask:0xf bank_mask:0xf bound_ctrl:1
	s_lshl_b32 s22, s20, 12
	v_pk_add_f32 v[2:3], v[2:3], v[28:29]
	s_cmp_eq_u32 s20, 1
	v_lshl_add_u32 v1, v97, 2, s21
	v_mov_b32_dpp v28, v2 quad_perm:[2,3,0,1] row_mask:0xf bank_mask:0xf bound_ctrl:1
	v_mov_b32_dpp v29, v3 quad_perm:[2,3,0,1] row_mask:0xf bank_mask:0xf bound_ctrl:1
	s_cselect_b32 s20, 0x6000, 0
	v_pk_add_f32 v[2:3], v[2:3], v[28:29]
	v_lshl_add_u32 v73, v98, 2, s21
	v_add_u32_e32 v74, s20, v143
	ds_read_b128 v[152:155], v1 offset:6912
	ds_read_b128 v[156:159], v1 offset:6928
	ds_read_b128 v[166:169], v1 offset:11008
	ds_read_b128 v[170:173], v1 offset:11024
	ds_read_b128 v[174:177], v1 offset:15104
	ds_read_b128 v[178:181], v1 offset:15120
	ds_read_b128 v[198:201], v1 offset:19200
	ds_read_b128 v[202:205], v1 offset:19216
	ds_read_b64 v[160:161], v73 offset:23296
	ds_read_b128 v[40:43], v74 offset:3072
	ds_read_b128 v[36:39], v74 offset:3088
	v_mov_b32_dpp v28, v2 row_half_mirror row_mask:0xf bank_mask:0xf bound_ctrl:1
	v_mov_b32_dpp v29, v3 row_half_mirror row_mask:0xf bank_mask:0xf bound_ctrl:1
	v_pk_add_f32 v[28:29], v[2:3], v[28:29]
	s_waitcnt lgkmcnt(6)
	v_pk_mul_f32 v[2:3], v[166:167], v[28:29] op_sel_hi:[0,1]
	s_waitcnt lgkmcnt(2)
	v_pk_fma_f32 v[2:3], v[174:175], v[160:161], v[2:3] op_sel_hi:[0,1,1] neg_lo:[0,0,1] neg_hi:[0,0,1]
	v_pk_fma_f32 v[2:3], v[70:71], v[152:153], v[2:3] op_sel_hi:[1,0,1]
	v_pk_mul_f32 v[30:31], v[166:167], v[28:29] op_sel:[1,0]
	v_pk_mul_f32 v[34:35], v[168:169], v[28:29] op_sel_hi:[0,1]
	v_pk_fma_f32 v[30:31], v[174:175], v[160:161], v[30:31] op_sel:[1,0,0] neg_lo:[0,0,1] neg_hi:[0,0,1]
	v_pk_fma_f32 v[34:35], v[176:177], v[160:161], v[34:35] op_sel_hi:[0,1,1] neg_lo:[0,0,1] neg_hi:[0,0,1]
	v_pk_mul_f32 v[70:71], v[168:169], v[28:29] op_sel:[1,0]
	v_pk_fma_f32 v[68:69], v[68:69], v[152:153], v[30:31] op_sel:[0,1,0]
	v_pk_fma_f32 v[66:67], v[66:67], v[154:155], v[34:35] op_sel_hi:[1,0,1]
	v_pk_fma_f32 v[70:71], v[176:177], v[160:161], v[70:71] op_sel:[1,0,0] neg_lo:[0,0,1] neg_hi:[0,0,1]
	v_pk_fma_f32 v[32:33], v[198:199], v[68:69], 0 op_sel:[1,0,0] op_sel_hi:[1,1,0]
	v_pk_fma_f32 v[64:65], v[64:65], v[154:155], v[70:71] op_sel:[0,1,0]
	v_pk_fma_f32 v[32:33], v[200:201], v[64:65], v[32:33] op_sel:[1,0,0]
	v_pk_mul_f32 v[34:35], v[170:171], v[28:29] op_sel_hi:[0,1]
	v_pk_fma_f32 v[34:35], v[178:179], v[160:161], v[34:35] op_sel_hi:[0,1,1] neg_lo:[0,0,1] neg_hi:[0,0,1]
	v_pk_fma_f32 v[62:63], v[62:63], v[156:157], v[34:35] op_sel_hi:[1,0,1]
	v_pk_mul_f32 v[34:35], v[170:171], v[28:29] op_sel:[1,0]
	v_pk_fma_f32 v[30:31], v[198:199], v[2:3], 0 op_sel_hi:[0,1,0]
	v_pk_fma_f32 v[34:35], v[178:179], v[160:161], v[34:35] op_sel:[1,0,0] neg_lo:[0,0,1] neg_hi:[0,0,1]
	v_pk_fma_f32 v[60:61], v[60:61], v[156:157], v[34:35] op_sel:[0,1,0]
	v_pk_mul_f32 v[34:35], v[172:173], v[28:29] op_sel_hi:[0,1]
	v_pk_fma_f32 v[30:31], v[200:201], v[66:67], v[30:31] op_sel_hi:[0,1,1]
	v_pk_fma_f32 v[34:35], v[180:181], v[160:161], v[34:35] op_sel_hi:[0,1,1] neg_lo:[0,0,1] neg_hi:[0,0,1]
	v_pk_mul_f32 v[28:29], v[172:173], v[28:29] op_sel:[1,0]
	v_pk_fma_f32 v[30:31], v[202:203], v[62:63], v[30:31] op_sel_hi:[0,1,1]
	v_pk_fma_f32 v[46:47], v[46:47], v[158:159], v[34:35] op_sel_hi:[1,0,1]
	v_pk_fma_f32 v[28:29], v[180:181], v[160:161], v[28:29] op_sel:[1,0,0] neg_lo:[0,0,1] neg_hi:[0,0,1]
	v_pk_fma_f32 v[32:33], v[202:203], v[60:61], v[32:33] op_sel:[1,0,0]
	v_pk_fma_f32 v[44:45], v[44:45], v[158:159], v[28:29] op_sel:[0,1,0]
	v_pk_fma_f32 v[28:29], v[204:205], v[46:47], v[30:31] op_sel_hi:[0,1,1]
	v_pk_fma_f32 v[30:31], v[204:205], v[44:45], v[32:33] op_sel:[1,0,0]
	v_pk_add_f32 v[28:29], v[28:29], v[30:31]
	v_add_u32_e32 v72, s22, v99
	s_nop 0
	v_mov_b32_dpp v30, v28 quad_perm:[1,0,3,2] row_mask:0xf bank_mask:0xf bound_ctrl:1
	v_mov_b32_dpp v31, v29 quad_perm:[1,0,3,2] row_mask:0xf bank_mask:0xf bound_ctrl:1
	v_pk_add_f32 v[28:29], v[28:29], v[30:31]
	s_nop 1
	v_mov_b32_dpp v30, v28 quad_perm:[2,3,0,1] row_mask:0xf bank_mask:0xf bound_ctrl:1
	v_mov_b32_dpp v31, v29 quad_perm:[2,3,0,1] row_mask:0xf bank_mask:0xf bound_ctrl:1
	v_pk_add_f32 v[28:29], v[28:29], v[30:31]
	s_nop 1
	v_mov_b32_dpp v30, v28 row_half_mirror row_mask:0xf bank_mask:0xf bound_ctrl:1
	v_mov_b32_dpp v31, v29 row_half_mirror row_mask:0xf bank_mask:0xf bound_ctrl:1
	s_and_saveexec_b64 s[20:21], s[14:15]
	v_pk_add_f32 v[28:29], v[28:29], v[30:31]
	ds_write_b64 v72, v[28:29] offset:51968
	s_or_b64 exec, exec, s[20:21]
	s_waitcnt lgkmcnt(1)
	v_pk_mul_f32 v[160:161], v[42:43], v[66:67] op_sel_hi:[0,1]
	v_pk_fma_f32 v[160:161], v[40:41], v[2:3], v[160:161] op_sel_hi:[0,1,1]
	v_pk_mul_f32 v[42:43], v[42:43], v[64:65] op_sel:[1,0]
	v_pk_fma_f32 v[40:41], v[40:41], v[68:69], v[42:43] op_sel:[1,0,0]
	s_waitcnt lgkmcnt(0)
	v_pk_fma_f32 v[42:43], v[36:37], v[62:63], v[160:161] op_sel_hi:[0,1,1]
	v_pk_fma_f32 v[36:37], v[36:37], v[60:61], v[40:41] op_sel:[1,0,0]
	v_pk_fma_f32 v[40:41], v[38:39], v[46:47], v[42:43] op_sel_hi:[0,1,1]
	v_pk_fma_f32 v[36:37], v[38:39], v[44:45], v[36:37] op_sel:[1,0,0]
	v_pk_add_f32 v[36:37], v[40:41], v[36:37]
	ds_read_b128 v[152:155], v1 offset:7168
	ds_read_b128 v[156:159], v1 offset:7184
	ds_read_b128 v[166:169], v1 offset:11264
	ds_read_b128 v[170:173], v1 offset:11280
	ds_read_b128 v[174:177], v1 offset:15360
	ds_read_b128 v[178:181], v1 offset:15376
	ds_read_b128 v[198:201], v1 offset:19456
	ds_read_b128 v[202:205], v1 offset:19472
	ds_read_b64 v[70:71], v73 offset:23552
	ds_read_b128 v[32:35], v74 offset:3328
	ds_read_b128 v[28:31], v74 offset:3344
	v_mov_b32_dpp v38, v36 quad_perm:[1,0,3,2] row_mask:0xf bank_mask:0xf bound_ctrl:1
	v_mov_b32_dpp v39, v37 quad_perm:[1,0,3,2] row_mask:0xf bank_mask:0xf bound_ctrl:1
	v_pk_add_f32 v[36:37], v[36:37], v[38:39]
	s_nop 1
	v_mov_b32_dpp v38, v36 quad_perm:[2,3,0,1] row_mask:0xf bank_mask:0xf bound_ctrl:1
	v_mov_b32_dpp v39, v37 quad_perm:[2,3,0,1] row_mask:0xf bank_mask:0xf bound_ctrl:1
	v_pk_add_f32 v[36:37], v[36:37], v[38:39]
	s_nop 1
	v_mov_b32_dpp v38, v36 row_half_mirror row_mask:0xf bank_mask:0xf bound_ctrl:1
	v_mov_b32_dpp v39, v37 row_half_mirror row_mask:0xf bank_mask:0xf bound_ctrl:1
	v_pk_add_f32 v[36:37], v[36:37], v[38:39]
	s_waitcnt lgkmcnt(8)
	v_pk_mul_f32 v[38:39], v[166:167], v[36:37] op_sel_hi:[0,1]
	s_waitcnt lgkmcnt(2)
	v_pk_fma_f32 v[38:39], v[174:175], v[70:71], v[38:39] op_sel_hi:[0,1,1] neg_lo:[0,0,1] neg_hi:[0,0,1]
	v_pk_fma_f32 v[2:3], v[2:3], v[152:153], v[38:39] op_sel_hi:[1,0,1]
	v_pk_mul_f32 v[38:39], v[166:167], v[36:37] op_sel:[1,0]
	v_pk_mul_f32 v[42:43], v[168:169], v[36:37] op_sel_hi:[0,1]
	v_pk_fma_f32 v[38:39], v[174:175], v[70:71], v[38:39] op_sel:[1,0,0] neg_lo:[0,0,1] neg_hi:[0,0,1]
	v_pk_fma_f32 v[42:43], v[176:177], v[70:71], v[42:43] op_sel_hi:[0,1,1] neg_lo:[0,0,1] neg_hi:[0,0,1]
	v_pk_fma_f32 v[68:69], v[68:69], v[152:153], v[38:39] op_sel:[0,1,0]
	v_pk_fma_f32 v[66:67], v[66:67], v[154:155], v[42:43] op_sel_hi:[1,0,1]
	v_pk_mul_f32 v[152:153], v[168:169], v[36:37] op_sel:[1,0]
	v_pk_fma_f32 v[152:153], v[176:177], v[70:71], v[152:153] op_sel:[1,0,0] neg_lo:[0,0,1] neg_hi:[0,0,1]
	v_pk_fma_f32 v[40:41], v[198:199], v[68:69], 0 op_sel:[1,0,0] op_sel_hi:[1,1,0]
	v_pk_fma_f32 v[64:65], v[64:65], v[154:155], v[152:153] op_sel:[0,1,0]
	v_pk_fma_f32 v[40:41], v[200:201], v[64:65], v[40:41] op_sel:[1,0,0]
	v_pk_mul_f32 v[42:43], v[170:171], v[36:37] op_sel_hi:[0,1]
	v_pk_fma_f32 v[42:43], v[178:179], v[70:71], v[42:43] op_sel_hi:[0,1,1] neg_lo:[0,0,1] neg_hi:[0,0,1]
	v_pk_fma_f32 v[62:63], v[62:63], v[156:157], v[42:43] op_sel_hi:[1,0,1]
	v_pk_mul_f32 v[42:43], v[170:171], v[36:37] op_sel:[1,0]
	v_pk_fma_f32 v[38:39], v[198:199], v[2:3], 0 op_sel_hi:[0,1,0]
	v_pk_fma_f32 v[42:43], v[178:179], v[70:71], v[42:43] op_sel:[1,0,0] neg_lo:[0,0,1] neg_hi:[0,0,1]
	v_pk_fma_f32 v[60:61], v[60:61], v[156:157], v[42:43] op_sel:[0,1,0]
	v_pk_mul_f32 v[42:43], v[172:173], v[36:37] op_sel_hi:[0,1]
	v_pk_fma_f32 v[38:39], v[200:201], v[66:67], v[38:39] op_sel_hi:[0,1,1]
	v_pk_fma_f32 v[42:43], v[180:181], v[70:71], v[42:43] op_sel_hi:[0,1,1] neg_lo:[0,0,1] neg_hi:[0,0,1]
	v_pk_mul_f32 v[36:37], v[172:173], v[36:37] op_sel:[1,0]
	v_pk_fma_f32 v[38:39], v[202:203], v[62:63], v[38:39] op_sel_hi:[0,1,1]
	v_pk_fma_f32 v[46:47], v[46:47], v[158:159], v[42:43] op_sel_hi:[1,0,1]
	v_pk_fma_f32 v[36:37], v[180:181], v[70:71], v[36:37] op_sel:[1,0,0] neg_lo:[0,0,1] neg_hi:[0,0,1]
	v_pk_fma_f32 v[40:41], v[202:203], v[60:61], v[40:41] op_sel:[1,0,0]
	v_pk_fma_f32 v[44:45], v[44:45], v[158:159], v[36:37] op_sel:[0,1,0]
	v_pk_fma_f32 v[36:37], v[204:205], v[46:47], v[38:39] op_sel_hi:[0,1,1]
	v_pk_fma_f32 v[38:39], v[204:205], v[44:45], v[40:41] op_sel:[1,0,0]
	v_pk_add_f32 v[36:37], v[36:37], v[38:39]
	s_nop 1
	v_mov_b32_dpp v38, v36 quad_perm:[1,0,3,2] row_mask:0xf bank_mask:0xf bound_ctrl:1
	v_mov_b32_dpp v39, v37 quad_perm:[1,0,3,2] row_mask:0xf bank_mask:0xf bound_ctrl:1
	v_pk_add_f32 v[36:37], v[36:37], v[38:39]
	s_nop 1
	v_mov_b32_dpp v38, v36 quad_perm:[2,3,0,1] row_mask:0xf bank_mask:0xf bound_ctrl:1
	v_mov_b32_dpp v39, v37 quad_perm:[2,3,0,1] row_mask:0xf bank_mask:0xf bound_ctrl:1
	v_pk_add_f32 v[36:37], v[36:37], v[38:39]
	s_nop 1
	v_mov_b32_dpp v38, v36 row_half_mirror row_mask:0xf bank_mask:0xf bound_ctrl:1
	v_mov_b32_dpp v39, v37 row_half_mirror row_mask:0xf bank_mask:0xf bound_ctrl:1
	s_and_saveexec_b64 s[20:21], s[14:15]
	v_pk_add_f32 v[36:37], v[36:37], v[38:39]
	ds_write_b64 v72, v[36:37] offset:52224
	s_or_b64 exec, exec, s[20:21]
	s_waitcnt lgkmcnt(1)
	v_pk_mul_f32 v[160:161], v[34:35], v[66:67] op_sel_hi:[0,1]
	v_pk_fma_f32 v[160:161], v[32:33], v[2:3], v[160:161] op_sel_hi:[0,1,1]
	v_pk_mul_f32 v[34:35], v[34:35], v[64:65] op_sel:[1,0]
	v_pk_fma_f32 v[32:33], v[32:33], v[68:69], v[34:35] op_sel:[1,0,0]
	s_waitcnt lgkmcnt(0)
	v_pk_fma_f32 v[34:35], v[28:29], v[62:63], v[160:161] op_sel_hi:[0,1,1]
	v_pk_fma_f32 v[28:29], v[28:29], v[60:61], v[32:33] op_sel:[1,0,0]
	v_pk_fma_f32 v[32:33], v[30:31], v[46:47], v[34:35] op_sel_hi:[0,1,1]
	v_pk_fma_f32 v[28:29], v[30:31], v[44:45], v[28:29] op_sel:[1,0,0]
	v_pk_add_f32 v[28:29], v[32:33], v[28:29]
	ds_read_b128 v[152:155], v1 offset:7424
	ds_read_b128 v[156:159], v1 offset:7440
	ds_read_b128 v[166:169], v1 offset:11520
	ds_read_b128 v[170:173], v1 offset:11536
	ds_read_b128 v[174:177], v1 offset:15616
	ds_read_b128 v[178:181], v1 offset:15632
	ds_read_b128 v[198:201], v1 offset:19712
	ds_read_b128 v[202:205], v1 offset:19728
	ds_read_b64 v[70:71], v73 offset:23808
	ds_read_b128 v[40:43], v74 offset:3584
	ds_read_b128 v[36:39], v74 offset:3600
	v_mov_b32_dpp v30, v28 quad_perm:[1,0,3,2] row_mask:0xf bank_mask:0xf bound_ctrl:1
	v_mov_b32_dpp v31, v29 quad_perm:[1,0,3,2] row_mask:0xf bank_mask:0xf bound_ctrl:1
	v_pk_add_f32 v[28:29], v[28:29], v[30:31]
	s_nop 1
	v_mov_b32_dpp v30, v28 quad_perm:[2,3,0,1] row_mask:0xf bank_mask:0xf bound_ctrl:1
	v_mov_b32_dpp v31, v29 quad_perm:[2,3,0,1] row_mask:0xf bank_mask:0xf bound_ctrl:1
	v_pk_add_f32 v[28:29], v[28:29], v[30:31]
	s_nop 1
	v_mov_b32_dpp v30, v28 row_half_mirror row_mask:0xf bank_mask:0xf bound_ctrl:1
	v_mov_b32_dpp v31, v29 row_half_mirror row_mask:0xf bank_mask:0xf bound_ctrl:1
	v_pk_add_f32 v[28:29], v[28:29], v[30:31]
	s_waitcnt lgkmcnt(8)
	v_pk_mul_f32 v[30:31], v[166:167], v[28:29] op_sel_hi:[0,1]
	s_waitcnt lgkmcnt(2)
	v_pk_fma_f32 v[30:31], v[174:175], v[70:71], v[30:31] op_sel_hi:[0,1,1] neg_lo:[0,0,1] neg_hi:[0,0,1]
	v_pk_fma_f32 v[2:3], v[2:3], v[152:153], v[30:31] op_sel_hi:[1,0,1]
	v_pk_mul_f32 v[30:31], v[166:167], v[28:29] op_sel:[1,0]
	v_pk_mul_f32 v[34:35], v[168:169], v[28:29] op_sel_hi:[0,1]
	v_pk_fma_f32 v[30:31], v[174:175], v[70:71], v[30:31] op_sel:[1,0,0] neg_lo:[0,0,1] neg_hi:[0,0,1]
	v_pk_fma_f32 v[34:35], v[176:177], v[70:71], v[34:35] op_sel_hi:[0,1,1] neg_lo:[0,0,1] neg_hi:[0,0,1]
	v_pk_fma_f32 v[68:69], v[68:69], v[152:153], v[30:31] op_sel:[0,1,0]
	v_pk_fma_f32 v[66:67], v[66:67], v[154:155], v[34:35] op_sel_hi:[1,0,1]
	v_pk_mul_f32 v[152:153], v[168:169], v[28:29] op_sel:[1,0]
	v_pk_fma_f32 v[152:153], v[176:177], v[70:71], v[152:153] op_sel:[1,0,0] neg_lo:[0,0,1] neg_hi:[0,0,1]
	v_pk_fma_f32 v[32:33], v[198:199], v[68:69], 0 op_sel:[1,0,0] op_sel_hi:[1,1,0]
	v_pk_fma_f32 v[64:65], v[64:65], v[154:155], v[152:153] op_sel:[0,1,0]
	v_pk_fma_f32 v[32:33], v[200:201], v[64:65], v[32:33] op_sel:[1,0,0]
	v_pk_mul_f32 v[34:35], v[170:171], v[28:29] op_sel_hi:[0,1]
	v_pk_fma_f32 v[34:35], v[178:179], v[70:71], v[34:35] op_sel_hi:[0,1,1] neg_lo:[0,0,1] neg_hi:[0,0,1]
	v_pk_fma_f32 v[62:63], v[62:63], v[156:157], v[34:35] op_sel_hi:[1,0,1]
	v_pk_mul_f32 v[34:35], v[170:171], v[28:29] op_sel:[1,0]
	v_pk_fma_f32 v[30:31], v[198:199], v[2:3], 0 op_sel_hi:[0,1,0]
	v_pk_fma_f32 v[34:35], v[178:179], v[70:71], v[34:35] op_sel:[1,0,0] neg_lo:[0,0,1] neg_hi:[0,0,1]
	v_pk_fma_f32 v[60:61], v[60:61], v[156:157], v[34:35] op_sel:[0,1,0]
	v_pk_mul_f32 v[34:35], v[172:173], v[28:29] op_sel_hi:[0,1]
	v_pk_fma_f32 v[30:31], v[200:201], v[66:67], v[30:31] op_sel_hi:[0,1,1]
	v_pk_fma_f32 v[34:35], v[180:181], v[70:71], v[34:35] op_sel_hi:[0,1,1] neg_lo:[0,0,1] neg_hi:[0,0,1]
	v_pk_mul_f32 v[28:29], v[172:173], v[28:29] op_sel:[1,0]
	v_pk_fma_f32 v[30:31], v[202:203], v[62:63], v[30:31] op_sel_hi:[0,1,1]
	v_pk_fma_f32 v[46:47], v[46:47], v[158:159], v[34:35] op_sel_hi:[1,0,1]
	v_pk_fma_f32 v[28:29], v[180:181], v[70:71], v[28:29] op_sel:[1,0,0] neg_lo:[0,0,1] neg_hi:[0,0,1]
	v_pk_fma_f32 v[32:33], v[202:203], v[60:61], v[32:33] op_sel:[1,0,0]
	v_pk_fma_f32 v[44:45], v[44:45], v[158:159], v[28:29] op_sel:[0,1,0]
	v_pk_fma_f32 v[28:29], v[204:205], v[46:47], v[30:31] op_sel_hi:[0,1,1]
	v_pk_fma_f32 v[30:31], v[204:205], v[44:45], v[32:33] op_sel:[1,0,0]
	v_pk_add_f32 v[28:29], v[28:29], v[30:31]
	s_nop 1
	v_mov_b32_dpp v30, v28 quad_perm:[1,0,3,2] row_mask:0xf bank_mask:0xf bound_ctrl:1
	v_mov_b32_dpp v31, v29 quad_perm:[1,0,3,2] row_mask:0xf bank_mask:0xf bound_ctrl:1
	v_pk_add_f32 v[28:29], v[28:29], v[30:31]
	s_nop 1
	v_mov_b32_dpp v30, v28 quad_perm:[2,3,0,1] row_mask:0xf bank_mask:0xf bound_ctrl:1
	v_mov_b32_dpp v31, v29 quad_perm:[2,3,0,1] row_mask:0xf bank_mask:0xf bound_ctrl:1
	v_pk_add_f32 v[28:29], v[28:29], v[30:31]
	s_nop 1
	v_mov_b32_dpp v30, v28 row_half_mirror row_mask:0xf bank_mask:0xf bound_ctrl:1
	v_mov_b32_dpp v31, v29 row_half_mirror row_mask:0xf bank_mask:0xf bound_ctrl:1
	s_and_saveexec_b64 s[20:21], s[14:15]
	v_pk_add_f32 v[28:29], v[28:29], v[30:31]
	ds_write_b64 v72, v[28:29] offset:52480
	s_or_b64 exec, exec, s[20:21]
	ds_read_b128 v[152:155], v1 offset:7680
	ds_read_b128 v[156:159], v1 offset:7696
	ds_read_b128 v[166:169], v1 offset:11776
	ds_read_b128 v[170:173], v1 offset:11792
	ds_read_b128 v[174:177], v1 offset:15872
	ds_read_b128 v[178:181], v1 offset:15888
	ds_read_b128 v[198:201], v1 offset:19968
	ds_read_b128 v[202:205], v1 offset:19984
	ds_read_b64 v[70:71], v73 offset:24064
	ds_read_b128 v[32:35], v74 offset:3840
	ds_read_b128 v[28:31], v74 offset:3856
	s_waitcnt lgkmcnt(12)
	v_pk_mul_f32 v[74:75], v[42:43], v[66:67] op_sel_hi:[0,1]
	v_pk_fma_f32 v[74:75], v[40:41], v[2:3], v[74:75] op_sel_hi:[0,1,1]
	v_pk_mul_f32 v[42:43], v[42:43], v[64:65] op_sel:[1,0]
	v_pk_fma_f32 v[40:41], v[40:41], v[68:69], v[42:43] op_sel:[1,0,0]
	s_waitcnt lgkmcnt(11)
	v_pk_fma_f32 v[42:43], v[36:37], v[62:63], v[74:75] op_sel_hi:[0,1,1]
	v_pk_fma_f32 v[36:37], v[36:37], v[60:61], v[40:41] op_sel:[1,0,0]
	v_pk_fma_f32 v[40:41], v[38:39], v[46:47], v[42:43] op_sel_hi:[0,1,1]
	v_pk_fma_f32 v[36:37], v[38:39], v[44:45], v[36:37] op_sel:[1,0,0]
	v_pk_add_f32 v[36:37], v[40:41], v[36:37]
	s_waitcnt lgkmcnt(10)
	v_mov_b32_dpp v38, v36 quad_perm:[1,0,3,2] row_mask:0xf bank_mask:0xf bound_ctrl:1
	v_mov_b32_dpp v39, v37 quad_perm:[1,0,3,2] row_mask:0xf bank_mask:0xf bound_ctrl:1
	v_pk_add_f32 v[36:37], v[36:37], v[38:39]
	s_nop 1
	v_mov_b32_dpp v38, v36 quad_perm:[2,3,0,1] row_mask:0xf bank_mask:0xf bound_ctrl:1
	v_mov_b32_dpp v39, v37 quad_perm:[2,3,0,1] row_mask:0xf bank_mask:0xf bound_ctrl:1
	v_pk_add_f32 v[36:37], v[36:37], v[38:39]
	s_nop 1
	v_mov_b32_dpp v38, v36 row_half_mirror row_mask:0xf bank_mask:0xf bound_ctrl:1
	v_mov_b32_dpp v39, v37 row_half_mirror row_mask:0xf bank_mask:0xf bound_ctrl:1
	v_pk_add_f32 v[74:75], v[36:37], v[38:39]
	s_waitcnt lgkmcnt(8)
	v_pk_mul_f32 v[36:37], v[166:167], v[74:75] op_sel_hi:[0,1]
	s_waitcnt lgkmcnt(2)
	v_pk_fma_f32 v[36:37], v[174:175], v[70:71], v[36:37] op_sel_hi:[0,1,1] neg_lo:[0,0,1] neg_hi:[0,0,1]
	v_pk_mul_f32 v[38:39], v[168:169], v[74:75] op_sel_hi:[0,1]
	v_pk_fma_f32 v[2:3], v[2:3], v[152:153], v[36:37] op_sel_hi:[1,0,1]
	v_pk_mul_f32 v[36:37], v[166:167], v[74:75] op_sel:[1,0]
	v_pk_fma_f32 v[38:39], v[176:177], v[70:71], v[38:39] op_sel_hi:[0,1,1] neg_lo:[0,0,1] neg_hi:[0,0,1]
	v_pk_fma_f32 v[36:37], v[174:175], v[70:71], v[36:37] op_sel:[1,0,0] neg_lo:[0,0,1] neg_hi:[0,0,1]
	v_pk_fma_f32 v[38:39], v[66:67], v[154:155], v[38:39] op_sel_hi:[1,0,1]
	v_pk_fma_f32 v[36:37], v[68:69], v[152:153], v[36:37] op_sel:[0,1,0]
	v_pk_mul_f32 v[66:67], v[168:169], v[74:75] op_sel:[1,0]
	v_pk_fma_f32 v[42:43], v[198:199], v[2:3], 0 op_sel_hi:[0,1,0]
	v_pk_fma_f32 v[66:67], v[176:177], v[70:71], v[66:67] op_sel:[1,0,0] neg_lo:[0,0,1] neg_hi:[0,0,1]
	v_pk_fma_f32 v[68:69], v[198:199], v[36:37], 0 op_sel:[1,0,0] op_sel_hi:[1,1,0]
	v_pk_fma_f32 v[40:41], v[64:65], v[154:155], v[66:67] op_sel:[0,1,0]
	v_pk_fma_f32 v[64:65], v[200:201], v[38:39], v[42:43] op_sel_hi:[0,1,1]
	v_pk_fma_f32 v[66:67], v[200:201], v[40:41], v[68:69] op_sel:[1,0,0]
	v_pk_mul_f32 v[42:43], v[170:171], v[74:75] op_sel_hi:[0,1]
	v_pk_fma_f32 v[42:43], v[178:179], v[70:71], v[42:43] op_sel_hi:[0,1,1] neg_lo:[0,0,1] neg_hi:[0,0,1]
	v_pk_fma_f32 v[42:43], v[62:63], v[156:157], v[42:43] op_sel_hi:[1,0,1]
	v_pk_mul_f32 v[62:63], v[170:171], v[74:75] op_sel:[1,0]
	v_pk_fma_f32 v[62:63], v[178:179], v[70:71], v[62:63] op_sel:[1,0,0] neg_lo:[0,0,1] neg_hi:[0,0,1]
	v_pk_fma_f32 v[60:61], v[60:61], v[156:157], v[62:63] op_sel:[0,1,0]
	v_pk_fma_f32 v[62:63], v[202:203], v[42:43], v[64:65] op_sel_hi:[0,1,1]
	v_pk_fma_f32 v[64:65], v[202:203], v[60:61], v[66:67] op_sel:[1,0,0]
	v_pk_mul_f32 v[66:67], v[172:173], v[74:75] op_sel_hi:[0,1]
	v_pk_fma_f32 v[66:67], v[180:181], v[70:71], v[66:67] op_sel_hi:[0,1,1] neg_lo:[0,0,1] neg_hi:[0,0,1]
	v_pk_mul_f32 v[68:69], v[172:173], v[74:75] op_sel:[1,0]
	v_pk_fma_f32 v[46:47], v[46:47], v[158:159], v[66:67] op_sel_hi:[1,0,1]
	v_pk_fma_f32 v[68:69], v[180:181], v[70:71], v[68:69] op_sel:[1,0,0] neg_lo:[0,0,1] neg_hi:[0,0,1]
	v_pk_fma_f32 v[44:45], v[44:45], v[158:159], v[68:69] op_sel:[0,1,0]
	v_pk_fma_f32 v[62:63], v[204:205], v[46:47], v[62:63] op_sel_hi:[0,1,1]
	v_pk_fma_f32 v[64:65], v[204:205], v[44:45], v[64:65] op_sel:[1,0,0]
	v_pk_add_f32 v[62:63], v[62:63], v[64:65]
	s_nop 1
	v_mov_b32_dpp v64, v62 quad_perm:[1,0,3,2] row_mask:0xf bank_mask:0xf bound_ctrl:1
	v_mov_b32_dpp v65, v63 quad_perm:[1,0,3,2] row_mask:0xf bank_mask:0xf bound_ctrl:1
	v_pk_add_f32 v[62:63], v[62:63], v[64:65]
	s_nop 1
	v_mov_b32_dpp v64, v62 quad_perm:[2,3,0,1] row_mask:0xf bank_mask:0xf bound_ctrl:1
	v_mov_b32_dpp v65, v63 quad_perm:[2,3,0,1] row_mask:0xf bank_mask:0xf bound_ctrl:1
	v_pk_add_f32 v[62:63], v[62:63], v[64:65]
	s_nop 1
	v_mov_b32_dpp v64, v62 row_half_mirror row_mask:0xf bank_mask:0xf bound_ctrl:1
	v_mov_b32_dpp v65, v63 row_half_mirror row_mask:0xf bank_mask:0xf bound_ctrl:1
	s_and_saveexec_b64 s[20:21], s[14:15]
	v_pk_add_f32 v[62:63], v[62:63], v[64:65]
	ds_write_b64 v72, v[62:63] offset:52736
	s_or_b64 exec, exec, s[20:21]
	s_waitcnt lgkmcnt(1)
	v_pk_mul_f32 v[66:67], v[34:35], v[38:39] op_sel_hi:[0,1]
	v_pk_mul_f32 v[68:69], v[34:35], v[40:41] op_sel:[1,0]
	v_pk_fma_f32 v[66:67], v[32:33], v[2:3], v[66:67] op_sel_hi:[0,1,1]
	v_pk_fma_f32 v[68:69], v[32:33], v[36:37], v[68:69] op_sel:[1,0,0]
	s_waitcnt lgkmcnt(0)
	v_pk_fma_f32 v[66:67], v[28:29], v[42:43], v[66:67] op_sel_hi:[0,1,1]
	v_pk_fma_f32 v[68:69], v[28:29], v[60:61], v[68:69] op_sel:[1,0,0]
	v_pk_fma_f32 v[66:67], v[30:31], v[46:47], v[66:67] op_sel_hi:[0,1,1]
	v_pk_fma_f32 v[68:69], v[30:31], v[44:45], v[68:69] op_sel:[1,0,0]
	v_pk_add_f32 v[66:67], v[66:67], v[68:69]
	ds_read_b64 v[74:75], v73 offset:24320
	ds_read_b128 v[152:155], v1 offset:20240
	ds_read_b128 v[156:159], v1 offset:20224
	ds_read_b128 v[166:169], v1 offset:16144
	ds_read_b128 v[62:65], v1 offset:16128
	ds_read_b128 v[170:173], v1 offset:12048
	ds_read_b128 v[174:177], v1 offset:12032
	ds_read_b128 v[178:181], v1 offset:7936
	ds_read_b128 v[198:201], v1 offset:7952
	v_mov_b32_dpp v68, v66 quad_perm:[1,0,3,2] row_mask:0xf bank_mask:0xf bound_ctrl:1
	v_mov_b32_dpp v69, v67 quad_perm:[1,0,3,2] row_mask:0xf bank_mask:0xf bound_ctrl:1
	v_pk_add_f32 v[66:67], v[66:67], v[68:69]
	s_nop 1
	v_mov_b32_dpp v68, v66 quad_perm:[2,3,0,1] row_mask:0xf bank_mask:0xf bound_ctrl:1
	v_mov_b32_dpp v69, v67 quad_perm:[2,3,0,1] row_mask:0xf bank_mask:0xf bound_ctrl:1
	v_pk_add_f32 v[66:67], v[66:67], v[68:69]
	s_nop 1
	v_mov_b32_dpp v68, v66 row_half_mirror row_mask:0xf bank_mask:0xf bound_ctrl:1
	v_mov_b32_dpp v69, v67 row_half_mirror row_mask:0xf bank_mask:0xf bound_ctrl:1
	v_pk_add_f32 v[160:161], v[66:67], v[68:69]
	s_waitcnt lgkmcnt(2)
	v_pk_mul_f32 v[66:67], v[174:175], v[160:161] op_sel_hi:[0,1]
	v_pk_fma_f32 v[66:67], v[74:75], v[62:63], v[66:67] op_sel_hi:[1,0,1] neg_lo:[0,0,1] neg_hi:[0,0,1]
	s_waitcnt lgkmcnt(1)
	v_pk_fma_f32 v[70:71], v[2:3], v[178:179], v[66:67] op_sel_hi:[1,0,1]
	v_pk_mul_f32 v[2:3], v[174:175], v[160:161] op_sel:[1,0]
	s_nop 0
	v_pk_fma_f32 v[2:3], v[74:75], v[62:63], v[2:3] op_sel:[0,1,0] neg_lo:[0,0,1] neg_hi:[0,0,1]
	v_pk_mul_f32 v[62:63], v[176:177], v[160:161] op_sel_hi:[0,1]
	v_pk_fma_f32 v[62:63], v[74:75], v[64:65], v[62:63] op_sel_hi:[1,0,1] neg_lo:[0,0,1] neg_hi:[0,0,1]
	v_pk_fma_f32 v[66:67], v[38:39], v[180:181], v[62:63] op_sel_hi:[1,0,1]
	v_pk_mul_f32 v[62:63], v[176:177], v[160:161] op_sel:[1,0]
	v_pk_fma_f32 v[68:69], v[36:37], v[178:179], v[2:3] op_sel:[0,1,0]
	v_pk_fma_f32 v[62:63], v[74:75], v[64:65], v[62:63] op_sel:[0,1,0] neg_lo:[0,0,1] neg_hi:[0,0,1]
	v_pk_fma_f32 v[36:37], v[156:157], v[68:69], 0 op_sel:[1,0,0] op_sel_hi:[1,1,0]
	v_pk_fma_f32 v[64:65], v[40:41], v[180:181], v[62:63] op_sel:[0,1,0]
	v_pk_fma_f32 v[36:37], v[158:159], v[64:65], v[36:37] op_sel:[1,0,0]
	v_pk_mul_f32 v[38:39], v[170:171], v[160:161] op_sel_hi:[0,1]
	v_pk_fma_f32 v[38:39], v[74:75], v[166:167], v[38:39] op_sel_hi:[1,0,1] neg_lo:[0,0,1] neg_hi:[0,0,1]
	s_waitcnt lgkmcnt(0)
	v_pk_fma_f32 v[62:63], v[42:43], v[198:199], v[38:39] op_sel_hi:[1,0,1]
	v_pk_mul_f32 v[38:39], v[170:171], v[160:161] op_sel:[1,0]
	v_pk_fma_f32 v[2:3], v[156:157], v[70:71], 0 op_sel_hi:[0,1,0]
	v_pk_fma_f32 v[38:39], v[74:75], v[166:167], v[38:39] op_sel:[0,1,0] neg_lo:[0,0,1] neg_hi:[0,0,1]
	v_mov_b32_e32 v42, v169
	v_pk_fma_f32 v[60:61], v[60:61], v[198:199], v[38:39] op_sel:[0,1,0]
	v_pk_mul_f32 v[38:39], v[172:173], v[160:161] op_sel_hi:[0,1]
	v_pk_fma_f32 v[38:39], v[74:75], v[168:169], v[38:39] op_sel_hi:[1,0,1] neg_lo:[0,0,1] neg_hi:[0,0,1]
	v_pk_mul_f32 v[40:41], v[172:173], v[160:161] op_sel:[1,0]
	v_pk_fma_f32 v[2:3], v[158:159], v[66:67], v[2:3] op_sel_hi:[0,1,1]
	v_pk_fma_f32 v[46:47], v[46:47], v[200:201], v[38:39] op_sel_hi:[1,0,1]
	v_pk_fma_f32 v[40:41], v[74:75], v[42:43], v[40:41] op_sel_hi:[1,0,1] neg_lo:[0,0,1] neg_hi:[0,0,1]
	v_pk_fma_f32 v[2:3], v[152:153], v[62:63], v[2:3] op_sel_hi:[0,1,1]
	v_pk_fma_f32 v[36:37], v[152:153], v[60:61], v[36:37] op_sel:[1,0,0]
	v_pk_fma_f32 v[44:45], v[44:45], v[200:201], v[40:41] op_sel:[0,1,0]
	v_mov_b32_e32 v38, v155
	v_pk_fma_f32 v[2:3], v[154:155], v[46:47], v[2:3] op_sel_hi:[0,1,1]
	v_pk_fma_f32 v[36:37], v[38:39], v[44:45], v[36:37] op_sel_hi:[0,1,1]
	v_pk_add_f32 v[2:3], v[2:3], v[36:37]
	s_nop 1
	v_mov_b32_dpp v36, v2 quad_perm:[1,0,3,2] row_mask:0xf bank_mask:0xf bound_ctrl:1
	v_mov_b32_dpp v37, v3 quad_perm:[1,0,3,2] row_mask:0xf bank_mask:0xf bound_ctrl:1
	v_pk_add_f32 v[2:3], v[2:3], v[36:37]
	s_nop 1
	v_mov_b32_dpp v36, v2 quad_perm:[2,3,0,1] row_mask:0xf bank_mask:0xf bound_ctrl:1
	v_mov_b32_dpp v37, v3 quad_perm:[2,3,0,1] row_mask:0xf bank_mask:0xf bound_ctrl:1
	v_pk_add_f32 v[2:3], v[2:3], v[36:37]
	s_nop 1
	v_mov_b32_dpp v36, v2 row_half_mirror row_mask:0xf bank_mask:0xf bound_ctrl:1
	v_mov_b32_dpp v37, v3 row_half_mirror row_mask:0xf bank_mask:0xf bound_ctrl:1
	s_and_saveexec_b64 s[20:21], s[14:15]
	s_cbranch_execz .LBB0_575
	v_pk_add_f32 v[2:3], v[2:3], v[36:37]
	ds_write_b64 v72, v[2:3] offset:52992
	s_branch .LBB0_575
